# P0 ada item rewritten: waves split M (own c m-tile), w_ada B fragments packed once per workgroup and shared through LDS (32 weight loads in flight per wave), no cross-wave tree reduction; pre-tiled bf
# speedup vs baseline: 1.0677x; 1.0037x over previous
.LBB0_30:
	v_readlane_b32 s3, v255, 5
	v_readlane_b32 s0, v255, 0
	v_readlane_b32 s1, v255, 1
	s_sub_u32 s0, s0, 0xc8
	s_subb_u32 s1, s1, 0
	s_load_dwordx2 s[74:75], s[0:1], 0x38
	v_lshrrev_b32_e32 v82, 4, v170
	s_lshl_b32 s73, s3, 7
	v_lshl_add_u32 v80, v82, 3, s73
	v_lshlrev_b32_e32 v83, 4, v170
	s_mul_i32 s73, s3, 0x3000
	v_add_u32_e32 v128, s73, v83
	v_mov_b32_e32 v129, v83
	v_add_u32_e32 v130, 0xc000, v83
	v_and_b32_e32 v134, 15, v170
	v_mul_u32_u24_e32 v134, 12, v134
	v_mov_b32_e32 v4, 0
	v_mov_b32_e32 v16, 0
	v_mov_b32_e32 v5, 0
	v_mov_b32_e32 v17, 0
	v_mov_b32_e32 v6, 0
	v_mov_b32_e32 v18, 0
	v_mov_b32_e32 v7, 0
	v_mov_b32_e32 v19, 0
	v_mov_b32_e32 v8, 0
	v_mov_b32_e32 v20, 0
	v_mov_b32_e32 v9, 0
	v_mov_b32_e32 v21, 0
	v_mov_b32_e32 v10, 0
	v_mov_b32_e32 v22, 0
	v_mov_b32_e32 v11, 0
	v_mov_b32_e32 v23, 0
	v_mov_b32_e32 v12, 0
	v_mov_b32_e32 v24, 0
	v_mov_b32_e32 v13, 0
	v_mov_b32_e32 v25, 0
	v_mov_b32_e32 v14, 0
	v_mov_b32_e32 v26, 0
	v_mov_b32_e32 v15, 0
	v_mov_b32_e32 v27, 0
	s_waitcnt lgkmcnt(0)
	s_mul_i32 s73, s95, 0xc0
	v_add_u32_e32 v82, s73, v134
	global_load_dwordx3 v[236:238], v82, s[74:75]
	s_waitcnt vmcnt(0)
	v_add_u32_e32 v82, 0, v80
	v_mad_u64_u32 v[2:3], s[0:1], v82, s69, v[226:227]
	global_load_dwordx3 v[28:30], v[2:3], off nt
	v_add_u32_e32 v82, 1, v80
	v_mad_u64_u32 v[2:3], s[0:1], v82, s69, v[226:227]
	global_load_dwordx3 v[32:34], v[2:3], off nt
	v_add_u32_e32 v82, 2, v80
	v_mad_u64_u32 v[2:3], s[0:1], v82, s69, v[226:227]
	global_load_dwordx3 v[36:38], v[2:3], off nt
	v_add_u32_e32 v82, 3, v80
	v_mad_u64_u32 v[2:3], s[0:1], v82, s69, v[226:227]
	global_load_dwordx3 v[40:42], v[2:3], off nt
	v_add_u32_e32 v82, 4, v80
	v_mad_u64_u32 v[2:3], s[0:1], v82, s69, v[226:227]
	global_load_dwordx3 v[44:46], v[2:3], off nt
	v_add_u32_e32 v82, 5, v80
	v_mad_u64_u32 v[2:3], s[0:1], v82, s69, v[226:227]
	global_load_dwordx3 v[48:50], v[2:3], off nt
	v_add_u32_e32 v82, 6, v80
	v_mad_u64_u32 v[2:3], s[0:1], v82, s69, v[226:227]
	global_load_dwordx3 v[52:54], v[2:3], off nt
	v_add_u32_e32 v82, 7, v80
	v_mad_u64_u32 v[2:3], s[0:1], v82, s69, v[226:227]
	global_load_dwordx3 v[56:58], v[2:3], off nt
	v_add_u32_e32 v82, 32, v80
	v_mad_u64_u32 v[2:3], s[0:1], v82, s69, v[226:227]
	global_load_dwordx3 v[60:62], v[2:3], off nt
	v_add_u32_e32 v82, 33, v80
	v_mad_u64_u32 v[2:3], s[0:1], v82, s69, v[226:227]
	global_load_dwordx3 v[64:66], v[2:3], off nt
	v_add_u32_e32 v82, 34, v80
	v_mad_u64_u32 v[2:3], s[0:1], v82, s69, v[226:227]
	global_load_dwordx3 v[68:70], v[2:3], off nt
	v_add_u32_e32 v82, 35, v80
	v_mad_u64_u32 v[2:3], s[0:1], v82, s69, v[226:227]
	global_load_dwordx3 v[72:74], v[2:3], off nt
	v_add_u32_e32 v82, 36, v80
	v_mad_u64_u32 v[2:3], s[0:1], v82, s69, v[226:227]
	global_load_dwordx3 v[76:78], v[2:3], off nt
	v_add_u32_e32 v82, 37, v80
	v_mad_u64_u32 v[2:3], s[0:1], v82, s69, v[226:227]
	global_load_dwordx3 v[84:86], v[2:3], off nt
	v_add_u32_e32 v82, 38, v80
	v_mad_u64_u32 v[2:3], s[0:1], v82, s69, v[226:227]
	global_load_dwordx3 v[88:90], v[2:3], off nt
	v_add_u32_e32 v82, 39, v80
	v_mad_u64_u32 v[2:3], s[0:1], v82, s69, v[226:227]
	global_load_dwordx3 v[92:94], v[2:3], off nt
	v_add_u32_e32 v82, 64, v80
	v_mad_u64_u32 v[2:3], s[0:1], v82, s69, v[226:227]
	global_load_dwordx3 v[96:98], v[2:3], off nt
	v_add_u32_e32 v82, 65, v80
	v_mad_u64_u32 v[2:3], s[0:1], v82, s69, v[226:227]
	global_load_dwordx3 v[100:102], v[2:3], off nt
	v_add_u32_e32 v82, 66, v80
	v_mad_u64_u32 v[2:3], s[0:1], v82, s69, v[226:227]
	global_load_dwordx3 v[104:106], v[2:3], off nt
	v_add_u32_e32 v82, 67, v80
	v_mad_u64_u32 v[2:3], s[0:1], v82, s69, v[226:227]
	global_load_dwordx3 v[108:110], v[2:3], off nt
	v_add_u32_e32 v82, 68, v80
	v_mad_u64_u32 v[2:3], s[0:1], v82, s69, v[226:227]
	global_load_dwordx3 v[112:114], v[2:3], off nt
	v_add_u32_e32 v82, 69, v80
	v_mad_u64_u32 v[2:3], s[0:1], v82, s69, v[226:227]
	global_load_dwordx3 v[116:118], v[2:3], off nt
	v_add_u32_e32 v82, 70, v80
	v_mad_u64_u32 v[2:3], s[0:1], v82, s69, v[226:227]
	global_load_dwordx3 v[120:122], v[2:3], off nt
	v_add_u32_e32 v82, 71, v80
	v_mad_u64_u32 v[2:3], s[0:1], v82, s69, v[226:227]
	global_load_dwordx3 v[124:126], v[2:3], off nt
	v_add_u32_e32 v82, 96, v80
	v_mad_u64_u32 v[2:3], s[0:1], v82, s69, v[226:227]
	global_load_dwordx3 v[140:142], v[2:3], off nt
	v_add_u32_e32 v82, 97, v80
	v_mad_u64_u32 v[2:3], s[0:1], v82, s69, v[226:227]
	global_load_dwordx3 v[144:146], v[2:3], off nt
	v_add_u32_e32 v82, 98, v80
	v_mad_u64_u32 v[2:3], s[0:1], v82, s69, v[226:227]
	global_load_dwordx3 v[148:150], v[2:3], off nt
	v_add_u32_e32 v82, 99, v80
	v_mad_u64_u32 v[2:3], s[0:1], v82, s69, v[226:227]
	global_load_dwordx3 v[152:154], v[2:3], off nt
	v_add_u32_e32 v82, 100, v80
	v_mad_u64_u32 v[2:3], s[0:1], v82, s69, v[226:227]
	global_load_dwordx3 v[160:162], v[2:3], off nt
	v_add_u32_e32 v82, 101, v80
	v_mad_u64_u32 v[2:3], s[0:1], v82, s69, v[226:227]
	global_load_dwordx3 v[164:166], v[2:3], off nt
	v_add_u32_e32 v82, 102, v80
	v_mad_u64_u32 v[2:3], s[0:1], v82, s69, v[226:227]
	global_load_dwordx3 v[172:174], v[2:3], off nt
	v_add_u32_e32 v82, 103, v80
	v_mad_u64_u32 v[2:3], s[0:1], v82, s69, v[226:227]
	global_load_dwordx3 v[176:178], v[2:3], off nt
	s_waitcnt vmcnt(24)
	v_cvt_pk_bf16_f32 v180, v28, v32
	v_cvt_pk_bf16_f32 v181, v36, v40
	v_cvt_pk_bf16_f32 v182, v44, v48
	v_cvt_pk_bf16_f32 v183, v52, v56
	v_cvt_pk_bf16_f32 v184, v29, v33
	v_cvt_pk_bf16_f32 v185, v37, v41
	v_cvt_pk_bf16_f32 v186, v45, v49
	v_cvt_pk_bf16_f32 v187, v53, v57
	v_cvt_pk_bf16_f32 v188, v30, v34
	v_cvt_pk_bf16_f32 v189, v38, v42
	v_cvt_pk_bf16_f32 v190, v46, v50
	v_cvt_pk_bf16_f32 v191, v54, v58
	ds_write_b128 v128, v[180:183] offset:0
	ds_write_b128 v128, v[184:187] offset:1024
	ds_write_b128 v128, v[188:191] offset:2048
	s_waitcnt vmcnt(16)
	v_cvt_pk_bf16_f32 v192, v60, v64
	v_cvt_pk_bf16_f32 v193, v68, v72
	v_cvt_pk_bf16_f32 v194, v76, v84
	v_cvt_pk_bf16_f32 v195, v88, v92
	v_cvt_pk_bf16_f32 v196, v61, v65
	v_cvt_pk_bf16_f32 v197, v69, v73
	v_cvt_pk_bf16_f32 v198, v77, v85
	v_cvt_pk_bf16_f32 v199, v89, v93
	v_cvt_pk_bf16_f32 v200, v62, v66
	v_cvt_pk_bf16_f32 v201, v70, v74
	v_cvt_pk_bf16_f32 v202, v78, v86
	v_cvt_pk_bf16_f32 v203, v90, v94
	ds_write_b128 v128, v[192:195] offset:3072
	ds_write_b128 v128, v[196:199] offset:4096
	ds_write_b128 v128, v[200:203] offset:5120
	s_waitcnt vmcnt(8)
	v_cvt_pk_bf16_f32 v204, v96, v100
	v_cvt_pk_bf16_f32 v205, v104, v108
	v_cvt_pk_bf16_f32 v206, v112, v116
	v_cvt_pk_bf16_f32 v207, v120, v124
	v_cvt_pk_bf16_f32 v208, v97, v101
	v_cvt_pk_bf16_f32 v209, v105, v109
	v_cvt_pk_bf16_f32 v210, v113, v117
	v_cvt_pk_bf16_f32 v211, v121, v125
	v_cvt_pk_bf16_f32 v212, v98, v102
	v_cvt_pk_bf16_f32 v213, v106, v110
	v_cvt_pk_bf16_f32 v214, v114, v118
	v_cvt_pk_bf16_f32 v215, v122, v126
	ds_write_b128 v128, v[204:207] offset:6144
	ds_write_b128 v128, v[208:211] offset:7168
	ds_write_b128 v128, v[212:215] offset:8192
	s_waitcnt vmcnt(0)
	v_cvt_pk_bf16_f32 v216, v140, v144
	v_cvt_pk_bf16_f32 v217, v148, v152
	v_cvt_pk_bf16_f32 v218, v160, v164
	v_cvt_pk_bf16_f32 v219, v172, v176
	v_cvt_pk_bf16_f32 v228, v141, v145
	v_cvt_pk_bf16_f32 v229, v149, v153
	v_cvt_pk_bf16_f32 v230, v161, v165
	v_cvt_pk_bf16_f32 v231, v173, v177
	v_cvt_pk_bf16_f32 v232, v142, v146
	v_cvt_pk_bf16_f32 v233, v150, v154
	v_cvt_pk_bf16_f32 v234, v162, v166
	v_cvt_pk_bf16_f32 v235, v174, v178
	ds_write_b128 v128, v[216:219] offset:9216
	ds_write_b128 v128, v[228:231] offset:10240
	ds_write_b128 v128, v[232:235] offset:11264
	s_waitcnt lgkmcnt(0)
	s_cmp_lg_u32 s3, 0
	s_cbranch_scc1 .Lp0a2_odd_sync
	v_mov_b32_e32 v132, 0x3f00
	s_mov_b32 s73, 0
.Lp0a2_odd_poll:
	global_load_dword v82, v132, s[70:71] sc1
	s_add_i32 s73, s73, 1
	s_waitcnt vmcnt(0)
	v_readfirstlane_b32 s93, v82
	s_cmp_ge_u32 s93, 576
	s_cbranch_scc1 .Lp0a2_odd_ok
	s_sleep 1
	s_cmp_lt_u32 s73, 0x8000
	s_cbranch_scc1 .Lp0a2_odd_poll

.Lp0a2_odd_sync:
	s_barrier
	s_lshl_b32 s73, s3, 10
	s_add_u32 s32, s70, 0x7800000
	s_addc_u32 s33, s71, 0
	s_add_u32 s32, s32, s73
	s_addc_u32 s33, s33, 0
	global_load_dwordx4 v[28:31], v83, s[32:33]
	s_add_u32 s32, s32, 0x2400
	s_addc_u32 s33, s33, 0
	global_load_dwordx4 v[32:35], v83, s[32:33]
	s_add_u32 s32, s32, 0x2400
	s_addc_u32 s33, s33, 0
	global_load_dwordx4 v[36:39], v83, s[32:33]
	s_add_u32 s32, s32, 0x2400
	s_addc_u32 s33, s33, 0
	global_load_dwordx4 v[40:43], v83, s[32:33]
	s_add_u32 s32, s32, 0x2400
	s_addc_u32 s33, s33, 0
	global_load_dwordx4 v[44:47], v83, s[32:33]
	s_add_u32 s32, s32, 0x2400
	s_addc_u32 s33, s33, 0
	global_load_dwordx4 v[48:51], v83, s[32:33]
	s_add_u32 s32, s32, 0x2400
	s_addc_u32 s33, s33, 0
	global_load_dwordx4 v[52:55], v83, s[32:33]
	s_add_u32 s32, s32, 0x2400
	s_addc_u32 s33, s33, 0
	global_load_dwordx4 v[56:59], v83, s[32:33]
	s_add_u32 s32, s32, 0x2400
	s_addc_u32 s33, s33, 0
	global_load_dwordx4 v[60:63], v83, s[32:33]
	s_add_u32 s32, s32, 0x2400
	s_addc_u32 s33, s33, 0
	global_load_dwordx4 v[64:67], v83, s[32:33]
	s_add_u32 s32, s32, 0x2400
	s_addc_u32 s33, s33, 0
	global_load_dwordx4 v[68:71], v83, s[32:33]
	s_add_u32 s32, s32, 0x2400
	s_addc_u32 s33, s33, 0
	global_load_dwordx4 v[72:75], v83, s[32:33]
	s_add_u32 s32, s32, 0x2400
	s_addc_u32 s33, s33, 0
	global_load_dwordx4 v[76:79], v83, s[32:33]
	s_add_u32 s32, s32, 0x2400
	s_addc_u32 s33, s33, 0
	global_load_dwordx4 v[84:87], v83, s[32:33]
	s_add_u32 s32, s32, 0x2400
	s_addc_u32 s33, s33, 0
	global_load_dwordx4 v[88:91], v83, s[32:33]
	s_add_u32 s32, s32, 0x2400
	s_addc_u32 s33, s33, 0
	global_load_dwordx4 v[92:95], v83, s[32:33]
	s_add_u32 s32, s32, 0x2400
	s_addc_u32 s33, s33, 0
	global_load_dwordx4 v[96:99], v83, s[32:33]
	s_add_u32 s32, s32, 0x2400
	s_addc_u32 s33, s33, 0
	global_load_dwordx4 v[100:103], v83, s[32:33]
	s_add_u32 s32, s32, 0x2400
	s_addc_u32 s33, s33, 0
	global_load_dwordx4 v[104:107], v83, s[32:33]
	s_add_u32 s32, s32, 0x2400
	s_addc_u32 s33, s33, 0
	global_load_dwordx4 v[108:111], v83, s[32:33]
	s_add_u32 s32, s32, 0x2400
	s_addc_u32 s33, s33, 0
	global_load_dwordx4 v[112:115], v83, s[32:33]
	s_add_u32 s32, s32, 0x2400
	s_addc_u32 s33, s33, 0
	global_load_dwordx4 v[116:119], v83, s[32:33]
	s_add_u32 s32, s32, 0x2400
	s_addc_u32 s33, s33, 0
	global_load_dwordx4 v[120:123], v83, s[32:33]
	s_add_u32 s32, s32, 0x2400
	s_addc_u32 s33, s33, 0
	global_load_dwordx4 v[124:127], v83, s[32:33]
	s_add_u32 s32, s32, 0x2400
	s_addc_u32 s33, s33, 0
	global_load_dwordx4 v[140:143], v83, s[32:33]
	s_add_u32 s32, s32, 0x2400
	s_addc_u32 s33, s33, 0
	global_load_dwordx4 v[144:147], v83, s[32:33]
	s_add_u32 s32, s32, 0x2400
	s_addc_u32 s33, s33, 0
	global_load_dwordx4 v[148:151], v83, s[32:33]
	s_add_u32 s32, s32, 0x2400
	s_addc_u32 s33, s33, 0
	global_load_dwordx4 v[152:155], v83, s[32:33]
	s_add_u32 s32, s32, 0x2400
	s_addc_u32 s33, s33, 0
	global_load_dwordx4 v[160:163], v83, s[32:33]
	s_add_u32 s32, s32, 0x2400
	s_addc_u32 s33, s33, 0
	global_load_dwordx4 v[164:167], v83, s[32:33]
	s_add_u32 s32, s32, 0x2400
	s_addc_u32 s33, s33, 0
	global_load_dwordx4 v[172:175], v83, s[32:33]
	s_add_u32 s32, s32, 0x2400
	s_addc_u32 s33, s33, 0
	global_load_dwordx4 v[176:179], v83, s[32:33]
	ds_read_b128 v[180:183], v129 offset:0
	ds_read_b128 v[184:187], v129 offset:1024
	ds_read_b128 v[188:191], v129 offset:2048
	ds_read_b128 v[192:195], v129 offset:3072
	ds_read_b128 v[196:199], v129 offset:4096
	ds_read_b128 v[200:203], v129 offset:5120
	ds_read_b128 v[204:207], v129 offset:6144
	ds_read_b128 v[208:211], v129 offset:7168
	ds_read_b128 v[212:215], v129 offset:8192
	ds_read_b128 v[216:219], v129 offset:9216
	ds_read_b128 v[228:231], v129 offset:10240
	ds_read_b128 v[232:235], v129 offset:11264
	s_waitcnt vmcnt(31)
	s_waitcnt lgkmcnt(9)
	v_mfma_f32_16x16x32_bf16 v[4:7], v[28:31], v[180:183], v[4:7]
	v_mfma_f32_16x16x32_bf16 v[8:11], v[28:31], v[184:187], v[8:11]
	v_mfma_f32_16x16x32_bf16 v[12:15], v[28:31], v[188:191], v[12:15]
	ds_read_b128 v[180:183], v129 offset:12288
	ds_read_b128 v[184:187], v129 offset:13312
	ds_read_b128 v[188:191], v129 offset:14336
	s_waitcnt vmcnt(30)
	s_waitcnt lgkmcnt(9)
	v_mfma_f32_16x16x32_bf16 v[4:7], v[32:35], v[192:195], v[4:7]
	v_mfma_f32_16x16x32_bf16 v[8:11], v[32:35], v[196:199], v[8:11]
	v_mfma_f32_16x16x32_bf16 v[12:15], v[32:35], v[200:203], v[12:15]
	ds_read_b128 v[192:195], v129 offset:15360
	ds_read_b128 v[196:199], v129 offset:16384
	ds_read_b128 v[200:203], v129 offset:17408
	s_waitcnt vmcnt(29)
	s_waitcnt lgkmcnt(9)
	v_mfma_f32_16x16x32_bf16 v[4:7], v[36:39], v[204:207], v[4:7]
	v_mfma_f32_16x16x32_bf16 v[8:11], v[36:39], v[208:211], v[8:11]
	v_mfma_f32_16x16x32_bf16 v[12:15], v[36:39], v[212:215], v[12:15]
	ds_read_b128 v[204:207], v129 offset:18432
	ds_read_b128 v[208:211], v129 offset:19456
	ds_read_b128 v[212:215], v129 offset:20480
	s_waitcnt vmcnt(28)
	s_waitcnt lgkmcnt(9)
	v_mfma_f32_16x16x32_bf16 v[4:7], v[40:43], v[216:219], v[4:7]
	v_mfma_f32_16x16x32_bf16 v[8:11], v[40:43], v[228:231], v[8:11]
	v_mfma_f32_16x16x32_bf16 v[12:15], v[40:43], v[232:235], v[12:15]
	ds_read_b128 v[216:219], v129 offset:21504
	ds_read_b128 v[228:231], v129 offset:22528
	ds_read_b128 v[232:235], v129 offset:23552
	s_waitcnt vmcnt(27)
	s_waitcnt lgkmcnt(9)
	v_mfma_f32_16x16x32_bf16 v[4:7], v[44:47], v[180:183], v[4:7]
	v_mfma_f32_16x16x32_bf16 v[8:11], v[44:47], v[184:187], v[8:11]
	v_mfma_f32_16x16x32_bf16 v[12:15], v[44:47], v[188:191], v[12:15]
	ds_read_b128 v[180:183], v129 offset:24576
	ds_read_b128 v[184:187], v129 offset:25600
	ds_read_b128 v[188:191], v129 offset:26624
	s_waitcnt vmcnt(26)
	s_waitcnt lgkmcnt(9)
	v_mfma_f32_16x16x32_bf16 v[4:7], v[48:51], v[192:195], v[4:7]
	v_mfma_f32_16x16x32_bf16 v[8:11], v[48:51], v[196:199], v[8:11]
	v_mfma_f32_16x16x32_bf16 v[12:15], v[48:51], v[200:203], v[12:15]
	ds_read_b128 v[192:195], v129 offset:27648
	ds_read_b128 v[196:199], v129 offset:28672
	ds_read_b128 v[200:203], v129 offset:29696
	s_waitcnt vmcnt(25)
	s_waitcnt lgkmcnt(9)
	v_mfma_f32_16x16x32_bf16 v[4:7], v[52:55], v[204:207], v[4:7]
	v_mfma_f32_16x16x32_bf16 v[8:11], v[52:55], v[208:211], v[8:11]
	v_mfma_f32_16x16x32_bf16 v[12:15], v[52:55], v[212:215], v[12:15]
	ds_read_b128 v[204:207], v129 offset:30720
	ds_read_b128 v[208:211], v129 offset:31744
	ds_read_b128 v[212:215], v129 offset:32768
	s_waitcnt vmcnt(24)
	s_waitcnt lgkmcnt(9)
	v_mfma_f32_16x16x32_bf16 v[4:7], v[56:59], v[216:219], v[4:7]
	v_mfma_f32_16x16x32_bf16 v[8:11], v[56:59], v[228:231], v[8:11]
	v_mfma_f32_16x16x32_bf16 v[12:15], v[56:59], v[232:235], v[12:15]
	ds_read_b128 v[216:219], v129 offset:33792
	ds_read_b128 v[228:231], v129 offset:34816
	ds_read_b128 v[232:235], v129 offset:35840
	s_waitcnt vmcnt(23)
	s_waitcnt lgkmcnt(9)
	v_mfma_f32_16x16x32_bf16 v[4:7], v[60:63], v[180:183], v[4:7]
	v_mfma_f32_16x16x32_bf16 v[8:11], v[60:63], v[184:187], v[8:11]
	v_mfma_f32_16x16x32_bf16 v[12:15], v[60:63], v[188:191], v[12:15]
	ds_read_b128 v[180:183], v129 offset:36864
	ds_read_b128 v[184:187], v129 offset:37888
	ds_read_b128 v[188:191], v129 offset:38912
	s_waitcnt vmcnt(22)
	s_waitcnt lgkmcnt(9)
	v_mfma_f32_16x16x32_bf16 v[4:7], v[64:67], v[192:195], v[4:7]
	v_mfma_f32_16x16x32_bf16 v[8:11], v[64:67], v[196:199], v[8:11]
	v_mfma_f32_16x16x32_bf16 v[12:15], v[64:67], v[200:203], v[12:15]
	ds_read_b128 v[192:195], v129 offset:39936
	ds_read_b128 v[196:199], v129 offset:40960
	ds_read_b128 v[200:203], v129 offset:41984
	s_waitcnt vmcnt(21)
	s_waitcnt lgkmcnt(9)
	v_mfma_f32_16x16x32_bf16 v[4:7], v[68:71], v[204:207], v[4:7]
	v_mfma_f32_16x16x32_bf16 v[8:11], v[68:71], v[208:211], v[8:11]
	v_mfma_f32_16x16x32_bf16 v[12:15], v[68:71], v[212:215], v[12:15]
	ds_read_b128 v[204:207], v129 offset:43008
	ds_read_b128 v[208:211], v129 offset:44032
	ds_read_b128 v[212:215], v129 offset:45056
	s_waitcnt vmcnt(20)
	s_waitcnt lgkmcnt(9)
	v_mfma_f32_16x16x32_bf16 v[4:7], v[72:75], v[216:219], v[4:7]
	v_mfma_f32_16x16x32_bf16 v[8:11], v[72:75], v[228:231], v[8:11]
	v_mfma_f32_16x16x32_bf16 v[12:15], v[72:75], v[232:235], v[12:15]
	ds_read_b128 v[216:219], v129 offset:46080
	ds_read_b128 v[228:231], v129 offset:47104
	ds_read_b128 v[232:235], v129 offset:48128
	s_waitcnt vmcnt(19)
	s_waitcnt lgkmcnt(9)
	v_mfma_f32_16x16x32_bf16 v[4:7], v[76:79], v[180:183], v[4:7]
	v_mfma_f32_16x16x32_bf16 v[8:11], v[76:79], v[184:187], v[8:11]
	v_mfma_f32_16x16x32_bf16 v[12:15], v[76:79], v[188:191], v[12:15]
	ds_read_b128 v[180:183], v130 offset:0
	ds_read_b128 v[184:187], v130 offset:1024
	ds_read_b128 v[188:191], v130 offset:2048
	s_waitcnt vmcnt(18)
	s_waitcnt lgkmcnt(9)
	v_mfma_f32_16x16x32_bf16 v[4:7], v[84:87], v[192:195], v[4:7]
	v_mfma_f32_16x16x32_bf16 v[8:11], v[84:87], v[196:199], v[8:11]
	v_mfma_f32_16x16x32_bf16 v[12:15], v[84:87], v[200:203], v[12:15]
	ds_read_b128 v[192:195], v130 offset:3072
	ds_read_b128 v[196:199], v130 offset:4096
	ds_read_b128 v[200:203], v130 offset:5120
	s_waitcnt vmcnt(17)
	s_waitcnt lgkmcnt(9)
	v_mfma_f32_16x16x32_bf16 v[4:7], v[88:91], v[204:207], v[4:7]
	v_mfma_f32_16x16x32_bf16 v[8:11], v[88:91], v[208:211], v[8:11]
	v_mfma_f32_16x16x32_bf16 v[12:15], v[88:91], v[212:215], v[12:15]
	ds_read_b128 v[204:207], v130 offset:6144
	ds_read_b128 v[208:211], v130 offset:7168
	ds_read_b128 v[212:215], v130 offset:8192
	s_waitcnt vmcnt(16)
	s_waitcnt lgkmcnt(9)
	v_mfma_f32_16x16x32_bf16 v[4:7], v[92:95], v[216:219], v[4:7]
	v_mfma_f32_16x16x32_bf16 v[8:11], v[92:95], v[228:231], v[8:11]
	v_mfma_f32_16x16x32_bf16 v[12:15], v[92:95], v[232:235], v[12:15]
	ds_read_b128 v[216:219], v130 offset:9216
	ds_read_b128 v[228:231], v130 offset:10240
	ds_read_b128 v[232:235], v130 offset:11264
	s_waitcnt vmcnt(15)
	s_waitcnt lgkmcnt(9)
	v_mfma_f32_16x16x32_bf16 v[4:7], v[96:99], v[180:183], v[4:7]
	v_mfma_f32_16x16x32_bf16 v[8:11], v[96:99], v[184:187], v[8:11]
	v_mfma_f32_16x16x32_bf16 v[12:15], v[96:99], v[188:191], v[12:15]
	ds_read_b128 v[180:183], v130 offset:12288
	ds_read_b128 v[184:187], v130 offset:13312
	ds_read_b128 v[188:191], v130 offset:14336
	s_waitcnt vmcnt(14)
	s_waitcnt lgkmcnt(9)
	v_mfma_f32_16x16x32_bf16 v[4:7], v[100:103], v[192:195], v[4:7]
	v_mfma_f32_16x16x32_bf16 v[8:11], v[100:103], v[196:199], v[8:11]
	v_mfma_f32_16x16x32_bf16 v[12:15], v[100:103], v[200:203], v[12:15]
	ds_read_b128 v[192:195], v130 offset:15360
	ds_read_b128 v[196:199], v130 offset:16384
	ds_read_b128 v[200:203], v130 offset:17408
	s_waitcnt vmcnt(13)
	s_waitcnt lgkmcnt(9)
	v_mfma_f32_16x16x32_bf16 v[4:7], v[104:107], v[204:207], v[4:7]
	v_mfma_f32_16x16x32_bf16 v[8:11], v[104:107], v[208:211], v[8:11]
	v_mfma_f32_16x16x32_bf16 v[12:15], v[104:107], v[212:215], v[12:15]
	ds_read_b128 v[204:207], v130 offset:18432
	ds_read_b128 v[208:211], v130 offset:19456
	ds_read_b128 v[212:215], v130 offset:20480
	s_waitcnt vmcnt(12)
	s_waitcnt lgkmcnt(9)
	v_mfma_f32_16x16x32_bf16 v[4:7], v[108:111], v[216:219], v[4:7]
	v_mfma_f32_16x16x32_bf16 v[8:11], v[108:111], v[228:231], v[8:11]
	v_mfma_f32_16x16x32_bf16 v[12:15], v[108:111], v[232:235], v[12:15]
	ds_read_b128 v[216:219], v130 offset:21504
	ds_read_b128 v[228:231], v130 offset:22528
	ds_read_b128 v[232:235], v130 offset:23552
	s_waitcnt vmcnt(11)
	s_waitcnt lgkmcnt(9)
	v_mfma_f32_16x16x32_bf16 v[4:7], v[112:115], v[180:183], v[4:7]
	v_mfma_f32_16x16x32_bf16 v[8:11], v[112:115], v[184:187], v[8:11]
	v_mfma_f32_16x16x32_bf16 v[12:15], v[112:115], v[188:191], v[12:15]
	ds_read_b128 v[180:183], v130 offset:24576
	ds_read_b128 v[184:187], v130 offset:25600
	ds_read_b128 v[188:191], v130 offset:26624
	s_waitcnt vmcnt(10)
	s_waitcnt lgkmcnt(9)
	v_mfma_f32_16x16x32_bf16 v[4:7], v[116:119], v[192:195], v[4:7]
	v_mfma_f32_16x16x32_bf16 v[8:11], v[116:119], v[196:199], v[8:11]
	v_mfma_f32_16x16x32_bf16 v[12:15], v[116:119], v[200:203], v[12:15]
	ds_read_b128 v[192:195], v130 offset:27648
	ds_read_b128 v[196:199], v130 offset:28672
	ds_read_b128 v[200:203], v130 offset:29696
	s_waitcnt vmcnt(9)
	s_waitcnt lgkmcnt(9)
	v_mfma_f32_16x16x32_bf16 v[4:7], v[120:123], v[204:207], v[4:7]
	v_mfma_f32_16x16x32_bf16 v[8:11], v[120:123], v[208:211], v[8:11]
	v_mfma_f32_16x16x32_bf16 v[12:15], v[120:123], v[212:215], v[12:15]
	ds_read_b128 v[204:207], v130 offset:30720
	ds_read_b128 v[208:211], v130 offset:31744
	ds_read_b128 v[212:215], v130 offset:32768
	s_waitcnt vmcnt(8)
	s_waitcnt lgkmcnt(9)
	v_mfma_f32_16x16x32_bf16 v[4:7], v[124:127], v[216:219], v[4:7]
	v_mfma_f32_16x16x32_bf16 v[8:11], v[124:127], v[228:231], v[8:11]
	v_mfma_f32_16x16x32_bf16 v[12:15], v[124:127], v[232:235], v[12:15]
	ds_read_b128 v[216:219], v130 offset:33792
	ds_read_b128 v[228:231], v130 offset:34816
	ds_read_b128 v[232:235], v130 offset:35840
	s_waitcnt vmcnt(7)
	s_waitcnt lgkmcnt(9)
	v_mfma_f32_16x16x32_bf16 v[4:7], v[140:143], v[180:183], v[4:7]
	v_mfma_f32_16x16x32_bf16 v[8:11], v[140:143], v[184:187], v[8:11]
	v_mfma_f32_16x16x32_bf16 v[12:15], v[140:143], v[188:191], v[12:15]
	ds_read_b128 v[180:183], v130 offset:36864
	ds_read_b128 v[184:187], v130 offset:37888
	ds_read_b128 v[188:191], v130 offset:38912
	s_waitcnt vmcnt(6)
	s_waitcnt lgkmcnt(9)
	v_mfma_f32_16x16x32_bf16 v[4:7], v[144:147], v[192:195], v[4:7]
	v_mfma_f32_16x16x32_bf16 v[8:11], v[144:147], v[196:199], v[8:11]
	v_mfma_f32_16x16x32_bf16 v[12:15], v[144:147], v[200:203], v[12:15]
	ds_read_b128 v[192:195], v130 offset:39936
	ds_read_b128 v[196:199], v130 offset:40960
	ds_read_b128 v[200:203], v130 offset:41984
	s_waitcnt vmcnt(5)
	s_waitcnt lgkmcnt(9)
	v_mfma_f32_16x16x32_bf16 v[4:7], v[148:151], v[204:207], v[4:7]
	v_mfma_f32_16x16x32_bf16 v[8:11], v[148:151], v[208:211], v[8:11]
	v_mfma_f32_16x16x32_bf16 v[12:15], v[148:151], v[212:215], v[12:15]
	ds_read_b128 v[204:207], v130 offset:43008
	ds_read_b128 v[208:211], v130 offset:44032
	ds_read_b128 v[212:215], v130 offset:45056
	s_waitcnt vmcnt(4)
	s_waitcnt lgkmcnt(9)
	v_mfma_f32_16x16x32_bf16 v[4:7], v[152:155], v[216:219], v[4:7]
	v_mfma_f32_16x16x32_bf16 v[8:11], v[152:155], v[228:231], v[8:11]
	v_mfma_f32_16x16x32_bf16 v[12:15], v[152:155], v[232:235], v[12:15]
	ds_read_b128 v[216:219], v130 offset:46080
	ds_read_b128 v[228:231], v130 offset:47104
	ds_read_b128 v[232:235], v130 offset:48128
	s_waitcnt vmcnt(3)
	s_waitcnt lgkmcnt(9)
	v_mfma_f32_16x16x32_bf16 v[4:7], v[160:163], v[180:183], v[4:7]
	v_mfma_f32_16x16x32_bf16 v[8:11], v[160:163], v[184:187], v[8:11]
	v_mfma_f32_16x16x32_bf16 v[12:15], v[160:163], v[188:191], v[12:15]
	s_waitcnt vmcnt(2)
	s_waitcnt lgkmcnt(6)
	v_mfma_f32_16x16x32_bf16 v[4:7], v[164:167], v[192:195], v[4:7]
	v_mfma_f32_16x16x32_bf16 v[8:11], v[164:167], v[196:199], v[8:11]
	v_mfma_f32_16x16x32_bf16 v[12:15], v[164:167], v[200:203], v[12:15]
	s_waitcnt vmcnt(1)
	s_waitcnt lgkmcnt(3)
	v_mfma_f32_16x16x32_bf16 v[4:7], v[172:175], v[204:207], v[4:7]
	v_mfma_f32_16x16x32_bf16 v[8:11], v[172:175], v[208:211], v[8:11]
	v_mfma_f32_16x16x32_bf16 v[12:15], v[172:175], v[212:215], v[12:15]
	s_waitcnt vmcnt(0)
	s_waitcnt lgkmcnt(0)
	v_mfma_f32_16x16x32_bf16 v[4:7], v[176:179], v[216:219], v[4:7]
	v_mfma_f32_16x16x32_bf16 v[8:11], v[176:179], v[228:231], v[8:11]
	v_mfma_f32_16x16x32_bf16 v[12:15], v[176:179], v[232:235], v[12:15]
	s_cmp_lg_u32 s3, 0
	s_cbranch_scc1 .Lp0a2_odd_nb0
	s_add_u32 s32, s70, 0x7802000
	s_addc_u32 s33, s71, 0
	global_load_dwordx4 v[28:31], v83, s[32:33]
	s_add_u32 s32, s32, 0x2400
	s_addc_u32 s33, s33, 0
	global_load_dwordx4 v[32:35], v83, s[32:33]
	s_add_u32 s32, s32, 0x2400
	s_addc_u32 s33, s33, 0
	global_load_dwordx4 v[36:39], v83, s[32:33]
	s_add_u32 s32, s32, 0x2400
	s_addc_u32 s33, s33, 0
	global_load_dwordx4 v[40:43], v83, s[32:33]
	s_add_u32 s32, s32, 0x2400
	s_addc_u32 s33, s33, 0
	global_load_dwordx4 v[44:47], v83, s[32:33]
	s_add_u32 s32, s32, 0x2400
	s_addc_u32 s33, s33, 0
	global_load_dwordx4 v[48:51], v83, s[32:33]
	s_add_u32 s32, s32, 0x2400
	s_addc_u32 s33, s33, 0
	global_load_dwordx4 v[52:55], v83, s[32:33]
	s_add_u32 s32, s32, 0x2400
	s_addc_u32 s33, s33, 0
	global_load_dwordx4 v[56:59], v83, s[32:33]
	s_add_u32 s32, s32, 0x2400
	s_addc_u32 s33, s33, 0
	global_load_dwordx4 v[60:63], v83, s[32:33]
	s_add_u32 s32, s32, 0x2400
	s_addc_u32 s33, s33, 0
	global_load_dwordx4 v[64:67], v83, s[32:33]
	s_add_u32 s32, s32, 0x2400
	s_addc_u32 s33, s33, 0
	global_load_dwordx4 v[68:71], v83, s[32:33]
	s_add_u32 s32, s32, 0x2400
	s_addc_u32 s33, s33, 0
	global_load_dwordx4 v[72:75], v83, s[32:33]
	s_add_u32 s32, s32, 0x2400
	s_addc_u32 s33, s33, 0
	global_load_dwordx4 v[76:79], v83, s[32:33]
	s_add_u32 s32, s32, 0x2400
	s_addc_u32 s33, s33, 0
	global_load_dwordx4 v[84:87], v83, s[32:33]
	s_add_u32 s32, s32, 0x2400
	s_addc_u32 s33, s33, 0
	global_load_dwordx4 v[88:91], v83, s[32:33]
	s_add_u32 s32, s32, 0x2400
	s_addc_u32 s33, s33, 0
	global_load_dwordx4 v[92:95], v83, s[32:33]
	s_add_u32 s32, s32, 0x2400
	s_addc_u32 s33, s33, 0
	global_load_dwordx4 v[96:99], v83, s[32:33]
	s_add_u32 s32, s32, 0x2400
	s_addc_u32 s33, s33, 0
	global_load_dwordx4 v[100:103], v83, s[32:33]
	s_add_u32 s32, s32, 0x2400
	s_addc_u32 s33, s33, 0
	global_load_dwordx4 v[104:107], v83, s[32:33]
	s_add_u32 s32, s32, 0x2400
	s_addc_u32 s33, s33, 0
	global_load_dwordx4 v[108:111], v83, s[32:33]
	s_add_u32 s32, s32, 0x2400
	s_addc_u32 s33, s33, 0
	global_load_dwordx4 v[112:115], v83, s[32:33]
	s_add_u32 s32, s32, 0x2400
	s_addc_u32 s33, s33, 0
	global_load_dwordx4 v[116:119], v83, s[32:33]
	s_add_u32 s32, s32, 0x2400
	s_addc_u32 s33, s33, 0
	global_load_dwordx4 v[120:123], v83, s[32:33]
	s_add_u32 s32, s32, 0x2400
	s_addc_u32 s33, s33, 0
	global_load_dwordx4 v[124:127], v83, s[32:33]
	s_add_u32 s32, s32, 0x2400
	s_addc_u32 s33, s33, 0
	global_load_dwordx4 v[140:143], v83, s[32:33]
	s_add_u32 s32, s32, 0x2400
	s_addc_u32 s33, s33, 0
	global_load_dwordx4 v[144:147], v83, s[32:33]
	s_add_u32 s32, s32, 0x2400
	s_addc_u32 s33, s33, 0
	global_load_dwordx4 v[148:151], v83, s[32:33]
	s_add_u32 s32, s32, 0x2400
	s_addc_u32 s33, s33, 0
	global_load_dwordx4 v[152:155], v83, s[32:33]
	s_add_u32 s32, s32, 0x2400
	s_addc_u32 s33, s33, 0
	global_load_dwordx4 v[160:163], v83, s[32:33]
	s_add_u32 s32, s32, 0x2400
	s_addc_u32 s33, s33, 0
	global_load_dwordx4 v[164:167], v83, s[32:33]
	s_add_u32 s32, s32, 0x2400
	s_addc_u32 s33, s33, 0
	global_load_dwordx4 v[172:175], v83, s[32:33]
	s_add_u32 s32, s32, 0x2400
	s_addc_u32 s33, s33, 0
	global_load_dwordx4 v[176:179], v83, s[32:33]
	ds_read_b128 v[180:183], v129 offset:0
	ds_read_b128 v[184:187], v129 offset:1024
	ds_read_b128 v[188:191], v129 offset:2048
	ds_read_b128 v[192:195], v129 offset:3072
	ds_read_b128 v[196:199], v129 offset:4096
	ds_read_b128 v[200:203], v129 offset:5120
	ds_read_b128 v[204:207], v129 offset:6144
	ds_read_b128 v[208:211], v129 offset:7168
	ds_read_b128 v[212:215], v129 offset:8192
	ds_read_b128 v[216:219], v129 offset:9216
	ds_read_b128 v[228:231], v129 offset:10240
	ds_read_b128 v[232:235], v129 offset:11264
	s_waitcnt vmcnt(31)
	s_waitcnt lgkmcnt(9)
	v_mfma_f32_16x16x32_bf16 v[16:19], v[28:31], v[180:183], v[16:19]
	v_mfma_f32_16x16x32_bf16 v[20:23], v[28:31], v[184:187], v[20:23]
	v_mfma_f32_16x16x32_bf16 v[24:27], v[28:31], v[188:191], v[24:27]
	ds_read_b128 v[180:183], v129 offset:12288
	ds_read_b128 v[184:187], v129 offset:13312
	ds_read_b128 v[188:191], v129 offset:14336
	s_waitcnt vmcnt(30)
	s_waitcnt lgkmcnt(9)
	v_mfma_f32_16x16x32_bf16 v[16:19], v[32:35], v[192:195], v[16:19]
	v_mfma_f32_16x16x32_bf16 v[20:23], v[32:35], v[196:199], v[20:23]
	v_mfma_f32_16x16x32_bf16 v[24:27], v[32:35], v[200:203], v[24:27]
	ds_read_b128 v[192:195], v129 offset:15360
	ds_read_b128 v[196:199], v129 offset:16384
	ds_read_b128 v[200:203], v129 offset:17408
	s_waitcnt vmcnt(29)
	s_waitcnt lgkmcnt(9)
	v_mfma_f32_16x16x32_bf16 v[16:19], v[36:39], v[204:207], v[16:19]
	v_mfma_f32_16x16x32_bf16 v[20:23], v[36:39], v[208:211], v[20:23]
	v_mfma_f32_16x16x32_bf16 v[24:27], v[36:39], v[212:215], v[24:27]
	ds_read_b128 v[204:207], v129 offset:18432
	ds_read_b128 v[208:211], v129 offset:19456
	ds_read_b128 v[212:215], v129 offset:20480
	s_waitcnt vmcnt(28)
	s_waitcnt lgkmcnt(9)
	v_mfma_f32_16x16x32_bf16 v[16:19], v[40:43], v[216:219], v[16:19]
	v_mfma_f32_16x16x32_bf16 v[20:23], v[40:43], v[228:231], v[20:23]
	v_mfma_f32_16x16x32_bf16 v[24:27], v[40:43], v[232:235], v[24:27]
	ds_read_b128 v[216:219], v129 offset:21504
	ds_read_b128 v[228:231], v129 offset:22528
	ds_read_b128 v[232:235], v129 offset:23552
	s_waitcnt vmcnt(27)
	s_waitcnt lgkmcnt(9)
	v_mfma_f32_16x16x32_bf16 v[16:19], v[44:47], v[180:183], v[16:19]
	v_mfma_f32_16x16x32_bf16 v[20:23], v[44:47], v[184:187], v[20:23]
	v_mfma_f32_16x16x32_bf16 v[24:27], v[44:47], v[188:191], v[24:27]
	ds_read_b128 v[180:183], v129 offset:24576
	ds_read_b128 v[184:187], v129 offset:25600
	ds_read_b128 v[188:191], v129 offset:26624
	s_waitcnt vmcnt(26)
	s_waitcnt lgkmcnt(9)
	v_mfma_f32_16x16x32_bf16 v[16:19], v[48:51], v[192:195], v[16:19]
	v_mfma_f32_16x16x32_bf16 v[20:23], v[48:51], v[196:199], v[20:23]
	v_mfma_f32_16x16x32_bf16 v[24:27], v[48:51], v[200:203], v[24:27]
	ds_read_b128 v[192:195], v129 offset:27648
	ds_read_b128 v[196:199], v129 offset:28672
	ds_read_b128 v[200:203], v129 offset:29696
	s_waitcnt vmcnt(25)
	s_waitcnt lgkmcnt(9)
	v_mfma_f32_16x16x32_bf16 v[16:19], v[52:55], v[204:207], v[16:19]
	v_mfma_f32_16x16x32_bf16 v[20:23], v[52:55], v[208:211], v[20:23]
	v_mfma_f32_16x16x32_bf16 v[24:27], v[52:55], v[212:215], v[24:27]
	ds_read_b128 v[204:207], v129 offset:30720
	ds_read_b128 v[208:211], v129 offset:31744
	ds_read_b128 v[212:215], v129 offset:32768
	s_waitcnt vmcnt(24)
	s_waitcnt lgkmcnt(9)
	v_mfma_f32_16x16x32_bf16 v[16:19], v[56:59], v[216:219], v[16:19]
	v_mfma_f32_16x16x32_bf16 v[20:23], v[56:59], v[228:231], v[20:23]
	v_mfma_f32_16x16x32_bf16 v[24:27], v[56:59], v[232:235], v[24:27]
	ds_read_b128 v[216:219], v129 offset:33792
	ds_read_b128 v[228:231], v129 offset:34816
	ds_read_b128 v[232:235], v129 offset:35840
	s_waitcnt vmcnt(23)
	s_waitcnt lgkmcnt(9)
	v_mfma_f32_16x16x32_bf16 v[16:19], v[60:63], v[180:183], v[16:19]
	v_mfma_f32_16x16x32_bf16 v[20:23], v[60:63], v[184:187], v[20:23]
	v_mfma_f32_16x16x32_bf16 v[24:27], v[60:63], v[188:191], v[24:27]
	ds_read_b128 v[180:183], v129 offset:36864
	ds_read_b128 v[184:187], v129 offset:37888
	ds_read_b128 v[188:191], v129 offset:38912
	s_waitcnt vmcnt(22)
	s_waitcnt lgkmcnt(9)
	v_mfma_f32_16x16x32_bf16 v[16:19], v[64:67], v[192:195], v[16:19]
	v_mfma_f32_16x16x32_bf16 v[20:23], v[64:67], v[196:199], v[20:23]
	v_mfma_f32_16x16x32_bf16 v[24:27], v[64:67], v[200:203], v[24:27]
	ds_read_b128 v[192:195], v129 offset:39936
	ds_read_b128 v[196:199], v129 offset:40960
	ds_read_b128 v[200:203], v129 offset:41984
	s_waitcnt vmcnt(21)
	s_waitcnt lgkmcnt(9)
	v_mfma_f32_16x16x32_bf16 v[16:19], v[68:71], v[204:207], v[16:19]
	v_mfma_f32_16x16x32_bf16 v[20:23], v[68:71], v[208:211], v[20:23]
	v_mfma_f32_16x16x32_bf16 v[24:27], v[68:71], v[212:215], v[24:27]
	ds_read_b128 v[204:207], v129 offset:43008
	ds_read_b128 v[208:211], v129 offset:44032
	ds_read_b128 v[212:215], v129 offset:45056
	s_waitcnt vmcnt(20)
	s_waitcnt lgkmcnt(9)
	v_mfma_f32_16x16x32_bf16 v[16:19], v[72:75], v[216:219], v[16:19]
	v_mfma_f32_16x16x32_bf16 v[20:23], v[72:75], v[228:231], v[20:23]
	v_mfma_f32_16x16x32_bf16 v[24:27], v[72:75], v[232:235], v[24:27]
	ds_read_b128 v[216:219], v129 offset:46080
	ds_read_b128 v[228:231], v129 offset:47104
	ds_read_b128 v[232:235], v129 offset:48128
	s_waitcnt vmcnt(19)
	s_waitcnt lgkmcnt(9)
	v_mfma_f32_16x16x32_bf16 v[16:19], v[76:79], v[180:183], v[16:19]
	v_mfma_f32_16x16x32_bf16 v[20:23], v[76:79], v[184:187], v[20:23]
	v_mfma_f32_16x16x32_bf16 v[24:27], v[76:79], v[188:191], v[24:27]
	ds_read_b128 v[180:183], v130 offset:0
	ds_read_b128 v[184:187], v130 offset:1024
	ds_read_b128 v[188:191], v130 offset:2048
	s_waitcnt vmcnt(18)
	s_waitcnt lgkmcnt(9)
	v_mfma_f32_16x16x32_bf16 v[16:19], v[84:87], v[192:195], v[16:19]
	v_mfma_f32_16x16x32_bf16 v[20:23], v[84:87], v[196:199], v[20:23]
	v_mfma_f32_16x16x32_bf16 v[24:27], v[84:87], v[200:203], v[24:27]
	ds_read_b128 v[192:195], v130 offset:3072
	ds_read_b128 v[196:199], v130 offset:4096
	ds_read_b128 v[200:203], v130 offset:5120
	s_waitcnt vmcnt(17)
	s_waitcnt lgkmcnt(9)
	v_mfma_f32_16x16x32_bf16 v[16:19], v[88:91], v[204:207], v[16:19]
	v_mfma_f32_16x16x32_bf16 v[20:23], v[88:91], v[208:211], v[20:23]
	v_mfma_f32_16x16x32_bf16 v[24:27], v[88:91], v[212:215], v[24:27]
	ds_read_b128 v[204:207], v130 offset:6144
	ds_read_b128 v[208:211], v130 offset:7168
	ds_read_b128 v[212:215], v130 offset:8192
	s_waitcnt vmcnt(16)
	s_waitcnt lgkmcnt(9)
	v_mfma_f32_16x16x32_bf16 v[16:19], v[92:95], v[216:219], v[16:19]
	v_mfma_f32_16x16x32_bf16 v[20:23], v[92:95], v[228:231], v[20:23]
	v_mfma_f32_16x16x32_bf16 v[24:27], v[92:95], v[232:235], v[24:27]
	ds_read_b128 v[216:219], v130 offset:9216
	ds_read_b128 v[228:231], v130 offset:10240
	ds_read_b128 v[232:235], v130 offset:11264
	s_waitcnt vmcnt(15)
	s_waitcnt lgkmcnt(9)
	v_mfma_f32_16x16x32_bf16 v[16:19], v[96:99], v[180:183], v[16:19]
	v_mfma_f32_16x16x32_bf16 v[20:23], v[96:99], v[184:187], v[20:23]
	v_mfma_f32_16x16x32_bf16 v[24:27], v[96:99], v[188:191], v[24:27]
	ds_read_b128 v[180:183], v130 offset:12288
	ds_read_b128 v[184:187], v130 offset:13312
	ds_read_b128 v[188:191], v130 offset:14336
	s_waitcnt vmcnt(14)
	s_waitcnt lgkmcnt(9)
	v_mfma_f32_16x16x32_bf16 v[16:19], v[100:103], v[192:195], v[16:19]
	v_mfma_f32_16x16x32_bf16 v[20:23], v[100:103], v[196:199], v[20:23]
	v_mfma_f32_16x16x32_bf16 v[24:27], v[100:103], v[200:203], v[24:27]
	ds_read_b128 v[192:195], v130 offset:15360
	ds_read_b128 v[196:199], v130 offset:16384
	ds_read_b128 v[200:203], v130 offset:17408
	s_waitcnt vmcnt(13)
	s_waitcnt lgkmcnt(9)
	v_mfma_f32_16x16x32_bf16 v[16:19], v[104:107], v[204:207], v[16:19]
	v_mfma_f32_16x16x32_bf16 v[20:23], v[104:107], v[208:211], v[20:23]
	v_mfma_f32_16x16x32_bf16 v[24:27], v[104:107], v[212:215], v[24:27]
	ds_read_b128 v[204:207], v130 offset:18432
	ds_read_b128 v[208:211], v130 offset:19456
	ds_read_b128 v[212:215], v130 offset:20480
	s_waitcnt vmcnt(12)
	s_waitcnt lgkmcnt(9)
	v_mfma_f32_16x16x32_bf16 v[16:19], v[108:111], v[216:219], v[16:19]
	v_mfma_f32_16x16x32_bf16 v[20:23], v[108:111], v[228:231], v[20:23]
	v_mfma_f32_16x16x32_bf16 v[24:27], v[108:111], v[232:235], v[24:27]
	ds_read_b128 v[216:219], v130 offset:21504
	ds_read_b128 v[228:231], v130 offset:22528
	ds_read_b128 v[232:235], v130 offset:23552
	s_waitcnt vmcnt(11)
	s_waitcnt lgkmcnt(9)
	v_mfma_f32_16x16x32_bf16 v[16:19], v[112:115], v[180:183], v[16:19]
	v_mfma_f32_16x16x32_bf16 v[20:23], v[112:115], v[184:187], v[20:23]
	v_mfma_f32_16x16x32_bf16 v[24:27], v[112:115], v[188:191], v[24:27]
	ds_read_b128 v[180:183], v130 offset:24576
	ds_read_b128 v[184:187], v130 offset:25600
	ds_read_b128 v[188:191], v130 offset:26624
	s_waitcnt vmcnt(10)
	s_waitcnt lgkmcnt(9)
	v_mfma_f32_16x16x32_bf16 v[16:19], v[116:119], v[192:195], v[16:19]
	v_mfma_f32_16x16x32_bf16 v[20:23], v[116:119], v[196:199], v[20:23]
	v_mfma_f32_16x16x32_bf16 v[24:27], v[116:119], v[200:203], v[24:27]
	ds_read_b128 v[192:195], v130 offset:27648
	ds_read_b128 v[196:199], v130 offset:28672
	ds_read_b128 v[200:203], v130 offset:29696
	s_waitcnt vmcnt(9)
	s_waitcnt lgkmcnt(9)
	v_mfma_f32_16x16x32_bf16 v[16:19], v[120:123], v[204:207], v[16:19]
	v_mfma_f32_16x16x32_bf16 v[20:23], v[120:123], v[208:211], v[20:23]
	v_mfma_f32_16x16x32_bf16 v[24:27], v[120:123], v[212:215], v[24:27]
	ds_read_b128 v[204:207], v130 offset:30720
	ds_read_b128 v[208:211], v130 offset:31744
	ds_read_b128 v[212:215], v130 offset:32768
	s_waitcnt vmcnt(8)
	s_waitcnt lgkmcnt(9)
	v_mfma_f32_16x16x32_bf16 v[16:19], v[124:127], v[216:219], v[16:19]
	v_mfma_f32_16x16x32_bf16 v[20:23], v[124:127], v[228:231], v[20:23]
	v_mfma_f32_16x16x32_bf16 v[24:27], v[124:127], v[232:235], v[24:27]
	ds_read_b128 v[216:219], v130 offset:33792
	ds_read_b128 v[228:231], v130 offset:34816
	ds_read_b128 v[232:235], v130 offset:35840
	s_waitcnt vmcnt(7)
	s_waitcnt lgkmcnt(9)
	v_mfma_f32_16x16x32_bf16 v[16:19], v[140:143], v[180:183], v[16:19]
	v_mfma_f32_16x16x32_bf16 v[20:23], v[140:143], v[184:187], v[20:23]
	v_mfma_f32_16x16x32_bf16 v[24:27], v[140:143], v[188:191], v[24:27]
	ds_read_b128 v[180:183], v130 offset:36864
	ds_read_b128 v[184:187], v130 offset:37888
	ds_read_b128 v[188:191], v130 offset:38912
	s_waitcnt vmcnt(6)
	s_waitcnt lgkmcnt(9)
	v_mfma_f32_16x16x32_bf16 v[16:19], v[144:147], v[192:195], v[16:19]
	v_mfma_f32_16x16x32_bf16 v[20:23], v[144:147], v[196:199], v[20:23]
	v_mfma_f32_16x16x32_bf16 v[24:27], v[144:147], v[200:203], v[24:27]
	ds_read_b128 v[192:195], v130 offset:39936
	ds_read_b128 v[196:199], v130 offset:40960
	ds_read_b128 v[200:203], v130 offset:41984
	s_waitcnt vmcnt(5)
	s_waitcnt lgkmcnt(9)
	v_mfma_f32_16x16x32_bf16 v[16:19], v[148:151], v[204:207], v[16:19]
	v_mfma_f32_16x16x32_bf16 v[20:23], v[148:151], v[208:211], v[20:23]
	v_mfma_f32_16x16x32_bf16 v[24:27], v[148:151], v[212:215], v[24:27]
	ds_read_b128 v[204:207], v130 offset:43008
	ds_read_b128 v[208:211], v130 offset:44032
	ds_read_b128 v[212:215], v130 offset:45056
	s_waitcnt vmcnt(4)
	s_waitcnt lgkmcnt(9)
	v_mfma_f32_16x16x32_bf16 v[16:19], v[152:155], v[216:219], v[16:19]
	v_mfma_f32_16x16x32_bf16 v[20:23], v[152:155], v[228:231], v[20:23]
	v_mfma_f32_16x16x32_bf16 v[24:27], v[152:155], v[232:235], v[24:27]
	ds_read_b128 v[216:219], v130 offset:46080
	ds_read_b128 v[228:231], v130 offset:47104
	ds_read_b128 v[232:235], v130 offset:48128
	s_waitcnt vmcnt(3)
	s_waitcnt lgkmcnt(9)
	v_mfma_f32_16x16x32_bf16 v[16:19], v[160:163], v[180:183], v[16:19]
	v_mfma_f32_16x16x32_bf16 v[20:23], v[160:163], v[184:187], v[20:23]
	v_mfma_f32_16x16x32_bf16 v[24:27], v[160:163], v[188:191], v[24:27]
	s_waitcnt vmcnt(2)
	s_waitcnt lgkmcnt(6)
	v_mfma_f32_16x16x32_bf16 v[16:19], v[164:167], v[192:195], v[16:19]
	v_mfma_f32_16x16x32_bf16 v[20:23], v[164:167], v[196:199], v[20:23]
	v_mfma_f32_16x16x32_bf16 v[24:27], v[164:167], v[200:203], v[24:27]
	s_waitcnt vmcnt(1)
	s_waitcnt lgkmcnt(3)
	v_mfma_f32_16x16x32_bf16 v[16:19], v[172:175], v[204:207], v[16:19]
	v_mfma_f32_16x16x32_bf16 v[20:23], v[172:175], v[208:211], v[20:23]
	v_mfma_f32_16x16x32_bf16 v[24:27], v[172:175], v[212:215], v[24:27]
	s_waitcnt vmcnt(0)
	s_waitcnt lgkmcnt(0)
	v_mfma_f32_16x16x32_bf16 v[16:19], v[176:179], v[216:219], v[16:19]
	v_mfma_f32_16x16x32_bf16 v[20:23], v[176:179], v[228:231], v[20:23]
	v_mfma_f32_16x16x32_bf16 v[24:27], v[176:179], v[232:235], v[24:27]
.Lp0a2_odd_nb0:
	s_waitcnt lgkmcnt(0)
	s_barrier
	v_add_u32_e32 v82, 1024, v80
	v_mad_u64_u32 v[2:3], s[0:1], v82, s69, v[226:227]
	global_load_dwordx3 v[28:30], v[2:3], off nt
	v_add_u32_e32 v82, 1025, v80
	v_mad_u64_u32 v[2:3], s[0:1], v82, s69, v[226:227]
	global_load_dwordx3 v[32:34], v[2:3], off nt
	v_add_u32_e32 v82, 1026, v80
	v_mad_u64_u32 v[2:3], s[0:1], v82, s69, v[226:227]
	global_load_dwordx3 v[36:38], v[2:3], off nt
	v_add_u32_e32 v82, 1027, v80
	v_mad_u64_u32 v[2:3], s[0:1], v82, s69, v[226:227]
	global_load_dwordx3 v[40:42], v[2:3], off nt
	v_add_u32_e32 v82, 1028, v80
	v_mad_u64_u32 v[2:3], s[0:1], v82, s69, v[226:227]
	global_load_dwordx3 v[44:46], v[2:3], off nt
	v_add_u32_e32 v82, 1029, v80
	v_mad_u64_u32 v[2:3], s[0:1], v82, s69, v[226:227]
	global_load_dwordx3 v[48:50], v[2:3], off nt
	v_add_u32_e32 v82, 1030, v80
	v_mad_u64_u32 v[2:3], s[0:1], v82, s69, v[226:227]
	global_load_dwordx3 v[52:54], v[2:3], off nt
	v_add_u32_e32 v82, 1031, v80
	v_mad_u64_u32 v[2:3], s[0:1], v82, s69, v[226:227]
	global_load_dwordx3 v[56:58], v[2:3], off nt
	v_add_u32_e32 v82, 1056, v80
	v_mad_u64_u32 v[2:3], s[0:1], v82, s69, v[226:227]
	global_load_dwordx3 v[60:62], v[2:3], off nt
	v_add_u32_e32 v82, 1057, v80
	v_mad_u64_u32 v[2:3], s[0:1], v82, s69, v[226:227]
	global_load_dwordx3 v[64:66], v[2:3], off nt
	v_add_u32_e32 v82, 1058, v80
	v_mad_u64_u32 v[2:3], s[0:1], v82, s69, v[226:227]
	global_load_dwordx3 v[68:70], v[2:3], off nt
	v_add_u32_e32 v82, 1059, v80
	v_mad_u64_u32 v[2:3], s[0:1], v82, s69, v[226:227]
	global_load_dwordx3 v[72:74], v[2:3], off nt
	v_add_u32_e32 v82, 1060, v80
	v_mad_u64_u32 v[2:3], s[0:1], v82, s69, v[226:227]
	global_load_dwordx3 v[76:78], v[2:3], off nt
	v_add_u32_e32 v82, 1061, v80
	v_mad_u64_u32 v[2:3], s[0:1], v82, s69, v[226:227]
	global_load_dwordx3 v[84:86], v[2:3], off nt
	v_add_u32_e32 v82, 1062, v80
	v_mad_u64_u32 v[2:3], s[0:1], v82, s69, v[226:227]
	global_load_dwordx3 v[88:90], v[2:3], off nt
	v_add_u32_e32 v82, 1063, v80
	v_mad_u64_u32 v[2:3], s[0:1], v82, s69, v[226:227]
	global_load_dwordx3 v[92:94], v[2:3], off nt
	v_add_u32_e32 v82, 1088, v80
	v_mad_u64_u32 v[2:3], s[0:1], v82, s69, v[226:227]
	global_load_dwordx3 v[96:98], v[2:3], off nt
	v_add_u32_e32 v82, 1089, v80
	v_mad_u64_u32 v[2:3], s[0:1], v82, s69, v[226:227]
	global_load_dwordx3 v[100:102], v[2:3], off nt
	v_add_u32_e32 v82, 1090, v80
	v_mad_u64_u32 v[2:3], s[0:1], v82, s69, v[226:227]
	global_load_dwordx3 v[104:106], v[2:3], off nt
	v_add_u32_e32 v82, 1091, v80
	v_mad_u64_u32 v[2:3], s[0:1], v82, s69, v[226:227]
	global_load_dwordx3 v[108:110], v[2:3], off nt
	v_add_u32_e32 v82, 1092, v80
	v_mad_u64_u32 v[2:3], s[0:1], v82, s69, v[226:227]
	global_load_dwordx3 v[112:114], v[2:3], off nt
	v_add_u32_e32 v82, 1093, v80
	v_mad_u64_u32 v[2:3], s[0:1], v82, s69, v[226:227]
	global_load_dwordx3 v[116:118], v[2:3], off nt
	v_add_u32_e32 v82, 1094, v80
	v_mad_u64_u32 v[2:3], s[0:1], v82, s69, v[226:227]
	global_load_dwordx3 v[120:122], v[2:3], off nt
	v_add_u32_e32 v82, 1095, v80
	v_mad_u64_u32 v[2:3], s[0:1], v82, s69, v[226:227]
	global_load_dwordx3 v[124:126], v[2:3], off nt
	v_add_u32_e32 v82, 1120, v80
	v_mad_u64_u32 v[2:3], s[0:1], v82, s69, v[226:227]
	global_load_dwordx3 v[140:142], v[2:3], off nt
	v_add_u32_e32 v82, 1121, v80
	v_mad_u64_u32 v[2:3], s[0:1], v82, s69, v[226:227]
	global_load_dwordx3 v[144:146], v[2:3], off nt
	v_add_u32_e32 v82, 1122, v80
	v_mad_u64_u32 v[2:3], s[0:1], v82, s69, v[226:227]
	global_load_dwordx3 v[148:150], v[2:3], off nt
	v_add_u32_e32 v82, 1123, v80
	v_mad_u64_u32 v[2:3], s[0:1], v82, s69, v[226:227]
	global_load_dwordx3 v[152:154], v[2:3], off nt
	v_add_u32_e32 v82, 1124, v80
	v_mad_u64_u32 v[2:3], s[0:1], v82, s69, v[226:227]
	global_load_dwordx3 v[160:162], v[2:3], off nt
	v_add_u32_e32 v82, 1125, v80
	v_mad_u64_u32 v[2:3], s[0:1], v82, s69, v[226:227]
	global_load_dwordx3 v[164:166], v[2:3], off nt
	v_add_u32_e32 v82, 1126, v80
	v_mad_u64_u32 v[2:3], s[0:1], v82, s69, v[226:227]
	global_load_dwordx3 v[172:174], v[2:3], off nt
	v_add_u32_e32 v82, 1127, v80
	v_mad_u64_u32 v[2:3], s[0:1], v82, s69, v[226:227]
	global_load_dwordx3 v[176:178], v[2:3], off nt
	s_waitcnt vmcnt(24)
	v_cvt_pk_bf16_f32 v180, v28, v32
	v_cvt_pk_bf16_f32 v181, v36, v40
	v_cvt_pk_bf16_f32 v182, v44, v48
	v_cvt_pk_bf16_f32 v183, v52, v56
	v_cvt_pk_bf16_f32 v184, v29, v33
	v_cvt_pk_bf16_f32 v185, v37, v41
	v_cvt_pk_bf16_f32 v186, v45, v49
	v_cvt_pk_bf16_f32 v187, v53, v57
	v_cvt_pk_bf16_f32 v188, v30, v34
	v_cvt_pk_bf16_f32 v189, v38, v42
	v_cvt_pk_bf16_f32 v190, v46, v50
	v_cvt_pk_bf16_f32 v191, v54, v58
	ds_write_b128 v128, v[180:183] offset:0
	ds_write_b128 v128, v[184:187] offset:1024
	ds_write_b128 v128, v[188:191] offset:2048
	s_waitcnt vmcnt(16)
	v_cvt_pk_bf16_f32 v192, v60, v64
	v_cvt_pk_bf16_f32 v193, v68, v72
	v_cvt_pk_bf16_f32 v194, v76, v84
	v_cvt_pk_bf16_f32 v195, v88, v92
	v_cvt_pk_bf16_f32 v196, v61, v65
	v_cvt_pk_bf16_f32 v197, v69, v73
	v_cvt_pk_bf16_f32 v198, v77, v85
	v_cvt_pk_bf16_f32 v199, v89, v93
	v_cvt_pk_bf16_f32 v200, v62, v66
	v_cvt_pk_bf16_f32 v201, v70, v74
	v_cvt_pk_bf16_f32 v202, v78, v86
	v_cvt_pk_bf16_f32 v203, v90, v94
	ds_write_b128 v128, v[192:195] offset:3072
	ds_write_b128 v128, v[196:199] offset:4096
	ds_write_b128 v128, v[200:203] offset:5120
	s_waitcnt vmcnt(8)
	v_cvt_pk_bf16_f32 v204, v96, v100
	v_cvt_pk_bf16_f32 v205, v104, v108
	v_cvt_pk_bf16_f32 v206, v112, v116
	v_cvt_pk_bf16_f32 v207, v120, v124
	v_cvt_pk_bf16_f32 v208, v97, v101
	v_cvt_pk_bf16_f32 v209, v105, v109
	v_cvt_pk_bf16_f32 v210, v113, v117
	v_cvt_pk_bf16_f32 v211, v121, v125
	v_cvt_pk_bf16_f32 v212, v98, v102
	v_cvt_pk_bf16_f32 v213, v106, v110
	v_cvt_pk_bf16_f32 v214, v114, v118
	v_cvt_pk_bf16_f32 v215, v122, v126
	ds_write_b128 v128, v[204:207] offset:6144
	ds_write_b128 v128, v[208:211] offset:7168
	ds_write_b128 v128, v[212:215] offset:8192
	s_waitcnt vmcnt(0)
	v_cvt_pk_bf16_f32 v216, v140, v144
	v_cvt_pk_bf16_f32 v217, v148, v152
	v_cvt_pk_bf16_f32 v218, v160, v164
	v_cvt_pk_bf16_f32 v219, v172, v176
	v_cvt_pk_bf16_f32 v228, v141, v145
	v_cvt_pk_bf16_f32 v229, v149, v153
	v_cvt_pk_bf16_f32 v230, v161, v165
	v_cvt_pk_bf16_f32 v231, v173, v177
	v_cvt_pk_bf16_f32 v232, v142, v146
	v_cvt_pk_bf16_f32 v233, v150, v154
	v_cvt_pk_bf16_f32 v234, v162, v166
	v_cvt_pk_bf16_f32 v235, v174, v178
	ds_write_b128 v128, v[216:219] offset:9216
	ds_write_b128 v128, v[228:231] offset:10240
	ds_write_b128 v128, v[232:235] offset:11264
	s_waitcnt lgkmcnt(0)
	s_barrier
	s_lshl_b32 s73, s3, 10
	s_add_u32 s32, s70, 0x7848000
	s_addc_u32 s33, s71, 0
	s_add_u32 s32, s32, s73
	s_addc_u32 s33, s33, 0
	global_load_dwordx4 v[28:31], v83, s[32:33]
	s_add_u32 s32, s32, 0x2400
	s_addc_u32 s33, s33, 0
	global_load_dwordx4 v[32:35], v83, s[32:33]
	s_add_u32 s32, s32, 0x2400
	s_addc_u32 s33, s33, 0
	global_load_dwordx4 v[36:39], v83, s[32:33]
	s_add_u32 s32, s32, 0x2400
	s_addc_u32 s33, s33, 0
	global_load_dwordx4 v[40:43], v83, s[32:33]
	s_add_u32 s32, s32, 0x2400
	s_addc_u32 s33, s33, 0
	global_load_dwordx4 v[44:47], v83, s[32:33]
	s_add_u32 s32, s32, 0x2400
	s_addc_u32 s33, s33, 0
	global_load_dwordx4 v[48:51], v83, s[32:33]
	s_add_u32 s32, s32, 0x2400
	s_addc_u32 s33, s33, 0
	global_load_dwordx4 v[52:55], v83, s[32:33]
	s_add_u32 s32, s32, 0x2400
	s_addc_u32 s33, s33, 0
	global_load_dwordx4 v[56:59], v83, s[32:33]
	s_add_u32 s32, s32, 0x2400
	s_addc_u32 s33, s33, 0
	global_load_dwordx4 v[60:63], v83, s[32:33]
	s_add_u32 s32, s32, 0x2400
	s_addc_u32 s33, s33, 0
	global_load_dwordx4 v[64:67], v83, s[32:33]
	s_add_u32 s32, s32, 0x2400
	s_addc_u32 s33, s33, 0
	global_load_dwordx4 v[68:71], v83, s[32:33]
	s_add_u32 s32, s32, 0x2400
	s_addc_u32 s33, s33, 0
	global_load_dwordx4 v[72:75], v83, s[32:33]
	s_add_u32 s32, s32, 0x2400
	s_addc_u32 s33, s33, 0
	global_load_dwordx4 v[76:79], v83, s[32:33]
	s_add_u32 s32, s32, 0x2400
	s_addc_u32 s33, s33, 0
	global_load_dwordx4 v[84:87], v83, s[32:33]
	s_add_u32 s32, s32, 0x2400
	s_addc_u32 s33, s33, 0
	global_load_dwordx4 v[88:91], v83, s[32:33]
	s_add_u32 s32, s32, 0x2400
	s_addc_u32 s33, s33, 0
	global_load_dwordx4 v[92:95], v83, s[32:33]
	s_add_u32 s32, s32, 0x2400
	s_addc_u32 s33, s33, 0
	global_load_dwordx4 v[96:99], v83, s[32:33]
	s_add_u32 s32, s32, 0x2400
	s_addc_u32 s33, s33, 0
	global_load_dwordx4 v[100:103], v83, s[32:33]
	s_add_u32 s32, s32, 0x2400
	s_addc_u32 s33, s33, 0
	global_load_dwordx4 v[104:107], v83, s[32:33]
	s_add_u32 s32, s32, 0x2400
	s_addc_u32 s33, s33, 0
	global_load_dwordx4 v[108:111], v83, s[32:33]
	s_add_u32 s32, s32, 0x2400
	s_addc_u32 s33, s33, 0
	global_load_dwordx4 v[112:115], v83, s[32:33]
	s_add_u32 s32, s32, 0x2400
	s_addc_u32 s33, s33, 0
	global_load_dwordx4 v[116:119], v83, s[32:33]
	s_add_u32 s32, s32, 0x2400
	s_addc_u32 s33, s33, 0
	global_load_dwordx4 v[120:123], v83, s[32:33]
	s_add_u32 s32, s32, 0x2400
	s_addc_u32 s33, s33, 0
	global_load_dwordx4 v[124:127], v83, s[32:33]
	s_add_u32 s32, s32, 0x2400
	s_addc_u32 s33, s33, 0
	global_load_dwordx4 v[140:143], v83, s[32:33]
	s_add_u32 s32, s32, 0x2400
	s_addc_u32 s33, s33, 0
	global_load_dwordx4 v[144:147], v83, s[32:33]
	s_add_u32 s32, s32, 0x2400
	s_addc_u32 s33, s33, 0
	global_load_dwordx4 v[148:151], v83, s[32:33]
	s_add_u32 s32, s32, 0x2400
	s_addc_u32 s33, s33, 0
	global_load_dwordx4 v[152:155], v83, s[32:33]
	s_add_u32 s32, s32, 0x2400
	s_addc_u32 s33, s33, 0
	global_load_dwordx4 v[160:163], v83, s[32:33]
	s_add_u32 s32, s32, 0x2400
	s_addc_u32 s33, s33, 0
	global_load_dwordx4 v[164:167], v83, s[32:33]
	s_add_u32 s32, s32, 0x2400
	s_addc_u32 s33, s33, 0
	global_load_dwordx4 v[172:175], v83, s[32:33]
	s_add_u32 s32, s32, 0x2400
	s_addc_u32 s33, s33, 0
	global_load_dwordx4 v[176:179], v83, s[32:33]
	ds_read_b128 v[180:183], v129 offset:0
	ds_read_b128 v[184:187], v129 offset:1024
	ds_read_b128 v[188:191], v129 offset:2048
	ds_read_b128 v[192:195], v129 offset:3072
	ds_read_b128 v[196:199], v129 offset:4096
	ds_read_b128 v[200:203], v129 offset:5120
	ds_read_b128 v[204:207], v129 offset:6144
	ds_read_b128 v[208:211], v129 offset:7168
	ds_read_b128 v[212:215], v129 offset:8192
	ds_read_b128 v[216:219], v129 offset:9216
	ds_read_b128 v[228:231], v129 offset:10240
	ds_read_b128 v[232:235], v129 offset:11264
	s_waitcnt vmcnt(31)
	s_waitcnt lgkmcnt(9)
	v_mfma_f32_16x16x32_bf16 v[4:7], v[28:31], v[180:183], v[4:7]
	v_mfma_f32_16x16x32_bf16 v[8:11], v[28:31], v[184:187], v[8:11]
	v_mfma_f32_16x16x32_bf16 v[12:15], v[28:31], v[188:191], v[12:15]
	ds_read_b128 v[180:183], v129 offset:12288
	ds_read_b128 v[184:187], v129 offset:13312
	ds_read_b128 v[188:191], v129 offset:14336
	s_waitcnt vmcnt(30)
	s_waitcnt lgkmcnt(9)
	v_mfma_f32_16x16x32_bf16 v[4:7], v[32:35], v[192:195], v[4:7]
	v_mfma_f32_16x16x32_bf16 v[8:11], v[32:35], v[196:199], v[8:11]
	v_mfma_f32_16x16x32_bf16 v[12:15], v[32:35], v[200:203], v[12:15]
	ds_read_b128 v[192:195], v129 offset:15360
	ds_read_b128 v[196:199], v129 offset:16384
	ds_read_b128 v[200:203], v129 offset:17408
	s_waitcnt vmcnt(29)
	s_waitcnt lgkmcnt(9)
	v_mfma_f32_16x16x32_bf16 v[4:7], v[36:39], v[204:207], v[4:7]
	v_mfma_f32_16x16x32_bf16 v[8:11], v[36:39], v[208:211], v[8:11]
	v_mfma_f32_16x16x32_bf16 v[12:15], v[36:39], v[212:215], v[12:15]
	ds_read_b128 v[204:207], v129 offset:18432
	ds_read_b128 v[208:211], v129 offset:19456
	ds_read_b128 v[212:215], v129 offset:20480
	s_waitcnt vmcnt(28)
	s_waitcnt lgkmcnt(9)
	v_mfma_f32_16x16x32_bf16 v[4:7], v[40:43], v[216:219], v[4:7]
	v_mfma_f32_16x16x32_bf16 v[8:11], v[40:43], v[228:231], v[8:11]
	v_mfma_f32_16x16x32_bf16 v[12:15], v[40:43], v[232:235], v[12:15]
	ds_read_b128 v[216:219], v129 offset:21504
	ds_read_b128 v[228:231], v129 offset:22528
	ds_read_b128 v[232:235], v129 offset:23552
	s_waitcnt vmcnt(27)
	s_waitcnt lgkmcnt(9)
	v_mfma_f32_16x16x32_bf16 v[4:7], v[44:47], v[180:183], v[4:7]
	v_mfma_f32_16x16x32_bf16 v[8:11], v[44:47], v[184:187], v[8:11]
	v_mfma_f32_16x16x32_bf16 v[12:15], v[44:47], v[188:191], v[12:15]
	ds_read_b128 v[180:183], v129 offset:24576
	ds_read_b128 v[184:187], v129 offset:25600
	ds_read_b128 v[188:191], v129 offset:26624
	s_waitcnt vmcnt(26)
	s_waitcnt lgkmcnt(9)
	v_mfma_f32_16x16x32_bf16 v[4:7], v[48:51], v[192:195], v[4:7]
	v_mfma_f32_16x16x32_bf16 v[8:11], v[48:51], v[196:199], v[8:11]
	v_mfma_f32_16x16x32_bf16 v[12:15], v[48:51], v[200:203], v[12:15]
	ds_read_b128 v[192:195], v129 offset:27648
	ds_read_b128 v[196:199], v129 offset:28672
	ds_read_b128 v[200:203], v129 offset:29696
	s_waitcnt vmcnt(25)
	s_waitcnt lgkmcnt(9)
	v_mfma_f32_16x16x32_bf16 v[4:7], v[52:55], v[204:207], v[4:7]
	v_mfma_f32_16x16x32_bf16 v[8:11], v[52:55], v[208:211], v[8:11]
	v_mfma_f32_16x16x32_bf16 v[12:15], v[52:55], v[212:215], v[12:15]
	ds_read_b128 v[204:207], v129 offset:30720
	ds_read_b128 v[208:211], v129 offset:31744
	ds_read_b128 v[212:215], v129 offset:32768
	s_waitcnt vmcnt(24)
	s_waitcnt lgkmcnt(9)
	v_mfma_f32_16x16x32_bf16 v[4:7], v[56:59], v[216:219], v[4:7]
	v_mfma_f32_16x16x32_bf16 v[8:11], v[56:59], v[228:231], v[8:11]
	v_mfma_f32_16x16x32_bf16 v[12:15], v[56:59], v[232:235], v[12:15]
	ds_read_b128 v[216:219], v129 offset:33792
	ds_read_b128 v[228:231], v129 offset:34816
	ds_read_b128 v[232:235], v129 offset:35840
	s_waitcnt vmcnt(23)
	s_waitcnt lgkmcnt(9)
	v_mfma_f32_16x16x32_bf16 v[4:7], v[60:63], v[180:183], v[4:7]
	v_mfma_f32_16x16x32_bf16 v[8:11], v[60:63], v[184:187], v[8:11]
	v_mfma_f32_16x16x32_bf16 v[12:15], v[60:63], v[188:191], v[12:15]
	ds_read_b128 v[180:183], v129 offset:36864
	ds_read_b128 v[184:187], v129 offset:37888
	ds_read_b128 v[188:191], v129 offset:38912
	s_waitcnt vmcnt(22)
	s_waitcnt lgkmcnt(9)
	v_mfma_f32_16x16x32_bf16 v[4:7], v[64:67], v[192:195], v[4:7]
	v_mfma_f32_16x16x32_bf16 v[8:11], v[64:67], v[196:199], v[8:11]
	v_mfma_f32_16x16x32_bf16 v[12:15], v[64:67], v[200:203], v[12:15]
	ds_read_b128 v[192:195], v129 offset:39936
	ds_read_b128 v[196:199], v129 offset:40960
	ds_read_b128 v[200:203], v129 offset:41984
	s_waitcnt vmcnt(21)
	s_waitcnt lgkmcnt(9)
	v_mfma_f32_16x16x32_bf16 v[4:7], v[68:71], v[204:207], v[4:7]
	v_mfma_f32_16x16x32_bf16 v[8:11], v[68:71], v[208:211], v[8:11]
	v_mfma_f32_16x16x32_bf16 v[12:15], v[68:71], v[212:215], v[12:15]
	ds_read_b128 v[204:207], v129 offset:43008
	ds_read_b128 v[208:211], v129 offset:44032
	ds_read_b128 v[212:215], v129 offset:45056
	s_waitcnt vmcnt(20)
	s_waitcnt lgkmcnt(9)
	v_mfma_f32_16x16x32_bf16 v[4:7], v[72:75], v[216:219], v[4:7]
	v_mfma_f32_16x16x32_bf16 v[8:11], v[72:75], v[228:231], v[8:11]
	v_mfma_f32_16x16x32_bf16 v[12:15], v[72:75], v[232:235], v[12:15]
	ds_read_b128 v[216:219], v129 offset:46080
	ds_read_b128 v[228:231], v129 offset:47104
	ds_read_b128 v[232:235], v129 offset:48128
	s_waitcnt vmcnt(19)
	s_waitcnt lgkmcnt(9)
	v_mfma_f32_16x16x32_bf16 v[4:7], v[76:79], v[180:183], v[4:7]
	v_mfma_f32_16x16x32_bf16 v[8:11], v[76:79], v[184:187], v[8:11]
	v_mfma_f32_16x16x32_bf16 v[12:15], v[76:79], v[188:191], v[12:15]
	ds_read_b128 v[180:183], v130 offset:0
	ds_read_b128 v[184:187], v130 offset:1024
	ds_read_b128 v[188:191], v130 offset:2048
	s_waitcnt vmcnt(18)
	s_waitcnt lgkmcnt(9)
	v_mfma_f32_16x16x32_bf16 v[4:7], v[84:87], v[192:195], v[4:7]
	v_mfma_f32_16x16x32_bf16 v[8:11], v[84:87], v[196:199], v[8:11]
	v_mfma_f32_16x16x32_bf16 v[12:15], v[84:87], v[200:203], v[12:15]
	ds_read_b128 v[192:195], v130 offset:3072
	ds_read_b128 v[196:199], v130 offset:4096
	ds_read_b128 v[200:203], v130 offset:5120
	s_waitcnt vmcnt(17)
	s_waitcnt lgkmcnt(9)
	v_mfma_f32_16x16x32_bf16 v[4:7], v[88:91], v[204:207], v[4:7]
	v_mfma_f32_16x16x32_bf16 v[8:11], v[88:91], v[208:211], v[8:11]
	v_mfma_f32_16x16x32_bf16 v[12:15], v[88:91], v[212:215], v[12:15]
	ds_read_b128 v[204:207], v130 offset:6144
	ds_read_b128 v[208:211], v130 offset:7168
	ds_read_b128 v[212:215], v130 offset:8192
	s_waitcnt vmcnt(16)
	s_waitcnt lgkmcnt(9)
	v_mfma_f32_16x16x32_bf16 v[4:7], v[92:95], v[216:219], v[4:7]
	v_mfma_f32_16x16x32_bf16 v[8:11], v[92:95], v[228:231], v[8:11]
	v_mfma_f32_16x16x32_bf16 v[12:15], v[92:95], v[232:235], v[12:15]
	ds_read_b128 v[216:219], v130 offset:9216
	ds_read_b128 v[228:231], v130 offset:10240
	ds_read_b128 v[232:235], v130 offset:11264
	s_waitcnt vmcnt(15)
	s_waitcnt lgkmcnt(9)
	v_mfma_f32_16x16x32_bf16 v[4:7], v[96:99], v[180:183], v[4:7]
	v_mfma_f32_16x16x32_bf16 v[8:11], v[96:99], v[184:187], v[8:11]
	v_mfma_f32_16x16x32_bf16 v[12:15], v[96:99], v[188:191], v[12:15]
	ds_read_b128 v[180:183], v130 offset:12288
	ds_read_b128 v[184:187], v130 offset:13312
	ds_read_b128 v[188:191], v130 offset:14336
	s_waitcnt vmcnt(14)
	s_waitcnt lgkmcnt(9)
	v_mfma_f32_16x16x32_bf16 v[4:7], v[100:103], v[192:195], v[4:7]
	v_mfma_f32_16x16x32_bf16 v[8:11], v[100:103], v[196:199], v[8:11]
	v_mfma_f32_16x16x32_bf16 v[12:15], v[100:103], v[200:203], v[12:15]
	ds_read_b128 v[192:195], v130 offset:15360
	ds_read_b128 v[196:199], v130 offset:16384
	ds_read_b128 v[200:203], v130 offset:17408
	s_waitcnt vmcnt(13)
	s_waitcnt lgkmcnt(9)
	v_mfma_f32_16x16x32_bf16 v[4:7], v[104:107], v[204:207], v[4:7]
	v_mfma_f32_16x16x32_bf16 v[8:11], v[104:107], v[208:211], v[8:11]
	v_mfma_f32_16x16x32_bf16 v[12:15], v[104:107], v[212:215], v[12:15]
	ds_read_b128 v[204:207], v130 offset:18432
	ds_read_b128 v[208:211], v130 offset:19456
	ds_read_b128 v[212:215], v130 offset:20480
	s_waitcnt vmcnt(12)
	s_waitcnt lgkmcnt(9)
	v_mfma_f32_16x16x32_bf16 v[4:7], v[108:111], v[216:219], v[4:7]
	v_mfma_f32_16x16x32_bf16 v[8:11], v[108:111], v[228:231], v[8:11]
	v_mfma_f32_16x16x32_bf16 v[12:15], v[108:111], v[232:235], v[12:15]
	ds_read_b128 v[216:219], v130 offset:21504
	ds_read_b128 v[228:231], v130 offset:22528
	ds_read_b128 v[232:235], v130 offset:23552
	s_waitcnt vmcnt(11)
	s_waitcnt lgkmcnt(9)
	v_mfma_f32_16x16x32_bf16 v[4:7], v[112:115], v[180:183], v[4:7]
	v_mfma_f32_16x16x32_bf16 v[8:11], v[112:115], v[184:187], v[8:11]
	v_mfma_f32_16x16x32_bf16 v[12:15], v[112:115], v[188:191], v[12:15]
	ds_read_b128 v[180:183], v130 offset:24576
	ds_read_b128 v[184:187], v130 offset:25600
	ds_read_b128 v[188:191], v130 offset:26624
	s_waitcnt vmcnt(10)
	s_waitcnt lgkmcnt(9)
	v_mfma_f32_16x16x32_bf16 v[4:7], v[116:119], v[192:195], v[4:7]
	v_mfma_f32_16x16x32_bf16 v[8:11], v[116:119], v[196:199], v[8:11]
	v_mfma_f32_16x16x32_bf16 v[12:15], v[116:119], v[200:203], v[12:15]
	ds_read_b128 v[192:195], v130 offset:27648
	ds_read_b128 v[196:199], v130 offset:28672
	ds_read_b128 v[200:203], v130 offset:29696
	s_waitcnt vmcnt(9)
	s_waitcnt lgkmcnt(9)
	v_mfma_f32_16x16x32_bf16 v[4:7], v[120:123], v[204:207], v[4:7]
	v_mfma_f32_16x16x32_bf16 v[8:11], v[120:123], v[208:211], v[8:11]
	v_mfma_f32_16x16x32_bf16 v[12:15], v[120:123], v[212:215], v[12:15]
	ds_read_b128 v[204:207], v130 offset:30720
	ds_read_b128 v[208:211], v130 offset:31744
	ds_read_b128 v[212:215], v130 offset:32768
	s_waitcnt vmcnt(8)
	s_waitcnt lgkmcnt(9)
	v_mfma_f32_16x16x32_bf16 v[4:7], v[124:127], v[216:219], v[4:7]
	v_mfma_f32_16x16x32_bf16 v[8:11], v[124:127], v[228:231], v[8:11]
	v_mfma_f32_16x16x32_bf16 v[12:15], v[124:127], v[232:235], v[12:15]
	ds_read_b128 v[216:219], v130 offset:33792
	ds_read_b128 v[228:231], v130 offset:34816
	ds_read_b128 v[232:235], v130 offset:35840
	s_waitcnt vmcnt(7)
	s_waitcnt lgkmcnt(9)
	v_mfma_f32_16x16x32_bf16 v[4:7], v[140:143], v[180:183], v[4:7]
	v_mfma_f32_16x16x32_bf16 v[8:11], v[140:143], v[184:187], v[8:11]
	v_mfma_f32_16x16x32_bf16 v[12:15], v[140:143], v[188:191], v[12:15]
	ds_read_b128 v[180:183], v130 offset:36864
	ds_read_b128 v[184:187], v130 offset:37888
	ds_read_b128 v[188:191], v130 offset:38912
	s_waitcnt vmcnt(6)
	s_waitcnt lgkmcnt(9)
	v_mfma_f32_16x16x32_bf16 v[4:7], v[144:147], v[192:195], v[4:7]
	v_mfma_f32_16x16x32_bf16 v[8:11], v[144:147], v[196:199], v[8:11]
	v_mfma_f32_16x16x32_bf16 v[12:15], v[144:147], v[200:203], v[12:15]
	ds_read_b128 v[192:195], v130 offset:39936
	ds_read_b128 v[196:199], v130 offset:40960
	ds_read_b128 v[200:203], v130 offset:41984
	s_waitcnt vmcnt(5)
	s_waitcnt lgkmcnt(9)
	v_mfma_f32_16x16x32_bf16 v[4:7], v[148:151], v[204:207], v[4:7]
	v_mfma_f32_16x16x32_bf16 v[8:11], v[148:151], v[208:211], v[8:11]
	v_mfma_f32_16x16x32_bf16 v[12:15], v[148:151], v[212:215], v[12:15]
	ds_read_b128 v[204:207], v130 offset:43008
	ds_read_b128 v[208:211], v130 offset:44032
	ds_read_b128 v[212:215], v130 offset:45056
	s_waitcnt vmcnt(4)
	s_waitcnt lgkmcnt(9)
	v_mfma_f32_16x16x32_bf16 v[4:7], v[152:155], v[216:219], v[4:7]
	v_mfma_f32_16x16x32_bf16 v[8:11], v[152:155], v[228:231], v[8:11]
	v_mfma_f32_16x16x32_bf16 v[12:15], v[152:155], v[232:235], v[12:15]
	ds_read_b128 v[216:219], v130 offset:46080
	ds_read_b128 v[228:231], v130 offset:47104
	ds_read_b128 v[232:235], v130 offset:48128
	s_waitcnt vmcnt(3)
	s_waitcnt lgkmcnt(9)
	v_mfma_f32_16x16x32_bf16 v[4:7], v[160:163], v[180:183], v[4:7]
	v_mfma_f32_16x16x32_bf16 v[8:11], v[160:163], v[184:187], v[8:11]
	v_mfma_f32_16x16x32_bf16 v[12:15], v[160:163], v[188:191], v[12:15]
	s_waitcnt vmcnt(2)
	s_waitcnt lgkmcnt(6)
	v_mfma_f32_16x16x32_bf16 v[4:7], v[164:167], v[192:195], v[4:7]
	v_mfma_f32_16x16x32_bf16 v[8:11], v[164:167], v[196:199], v[8:11]
	v_mfma_f32_16x16x32_bf16 v[12:15], v[164:167], v[200:203], v[12:15]
	s_waitcnt vmcnt(1)
	s_waitcnt lgkmcnt(3)
	v_mfma_f32_16x16x32_bf16 v[4:7], v[172:175], v[204:207], v[4:7]
	v_mfma_f32_16x16x32_bf16 v[8:11], v[172:175], v[208:211], v[8:11]
	v_mfma_f32_16x16x32_bf16 v[12:15], v[172:175], v[212:215], v[12:15]
	s_waitcnt vmcnt(0)
	s_waitcnt lgkmcnt(0)
	v_mfma_f32_16x16x32_bf16 v[4:7], v[176:179], v[216:219], v[4:7]
	v_mfma_f32_16x16x32_bf16 v[8:11], v[176:179], v[228:231], v[8:11]
	v_mfma_f32_16x16x32_bf16 v[12:15], v[176:179], v[232:235], v[12:15]
	s_cmp_lg_u32 s3, 0
	s_cbranch_scc1 .Lp0a2_odd_nb1
	s_add_u32 s32, s70, 0x784a000
	s_addc_u32 s33, s71, 0
	global_load_dwordx4 v[28:31], v83, s[32:33]
	s_add_u32 s32, s32, 0x2400
	s_addc_u32 s33, s33, 0
	global_load_dwordx4 v[32:35], v83, s[32:33]
	s_add_u32 s32, s32, 0x2400
	s_addc_u32 s33, s33, 0
	global_load_dwordx4 v[36:39], v83, s[32:33]
	s_add_u32 s32, s32, 0x2400
	s_addc_u32 s33, s33, 0
	global_load_dwordx4 v[40:43], v83, s[32:33]
	s_add_u32 s32, s32, 0x2400
	s_addc_u32 s33, s33, 0
	global_load_dwordx4 v[44:47], v83, s[32:33]
	s_add_u32 s32, s32, 0x2400
	s_addc_u32 s33, s33, 0
	global_load_dwordx4 v[48:51], v83, s[32:33]
	s_add_u32 s32, s32, 0x2400
	s_addc_u32 s33, s33, 0
	global_load_dwordx4 v[52:55], v83, s[32:33]
	s_add_u32 s32, s32, 0x2400
	s_addc_u32 s33, s33, 0
	global_load_dwordx4 v[56:59], v83, s[32:33]
	s_add_u32 s32, s32, 0x2400
	s_addc_u32 s33, s33, 0
	global_load_dwordx4 v[60:63], v83, s[32:33]
	s_add_u32 s32, s32, 0x2400
	s_addc_u32 s33, s33, 0
	global_load_dwordx4 v[64:67], v83, s[32:33]
	s_add_u32 s32, s32, 0x2400
	s_addc_u32 s33, s33, 0
	global_load_dwordx4 v[68:71], v83, s[32:33]
	s_add_u32 s32, s32, 0x2400
	s_addc_u32 s33, s33, 0
	global_load_dwordx4 v[72:75], v83, s[32:33]
	s_add_u32 s32, s32, 0x2400
	s_addc_u32 s33, s33, 0
	global_load_dwordx4 v[76:79], v83, s[32:33]
	s_add_u32 s32, s32, 0x2400
	s_addc_u32 s33, s33, 0
	global_load_dwordx4 v[84:87], v83, s[32:33]
	s_add_u32 s32, s32, 0x2400
	s_addc_u32 s33, s33, 0
	global_load_dwordx4 v[88:91], v83, s[32:33]
	s_add_u32 s32, s32, 0x2400
	s_addc_u32 s33, s33, 0
	global_load_dwordx4 v[92:95], v83, s[32:33]
	s_add_u32 s32, s32, 0x2400
	s_addc_u32 s33, s33, 0
	global_load_dwordx4 v[96:99], v83, s[32:33]
	s_add_u32 s32, s32, 0x2400
	s_addc_u32 s33, s33, 0
	global_load_dwordx4 v[100:103], v83, s[32:33]
	s_add_u32 s32, s32, 0x2400
	s_addc_u32 s33, s33, 0
	global_load_dwordx4 v[104:107], v83, s[32:33]
	s_add_u32 s32, s32, 0x2400
	s_addc_u32 s33, s33, 0
	global_load_dwordx4 v[108:111], v83, s[32:33]
	s_add_u32 s32, s32, 0x2400
	s_addc_u32 s33, s33, 0
	global_load_dwordx4 v[112:115], v83, s[32:33]
	s_add_u32 s32, s32, 0x2400
	s_addc_u32 s33, s33, 0
	global_load_dwordx4 v[116:119], v83, s[32:33]
	s_add_u32 s32, s32, 0x2400
	s_addc_u32 s33, s33, 0
	global_load_dwordx4 v[120:123], v83, s[32:33]
	s_add_u32 s32, s32, 0x2400
	s_addc_u32 s33, s33, 0
	global_load_dwordx4 v[124:127], v83, s[32:33]
	s_add_u32 s32, s32, 0x2400
	s_addc_u32 s33, s33, 0
	global_load_dwordx4 v[140:143], v83, s[32:33]
	s_add_u32 s32, s32, 0x2400
	s_addc_u32 s33, s33, 0
	global_load_dwordx4 v[144:147], v83, s[32:33]
	s_add_u32 s32, s32, 0x2400
	s_addc_u32 s33, s33, 0
	global_load_dwordx4 v[148:151], v83, s[32:33]
	s_add_u32 s32, s32, 0x2400
	s_addc_u32 s33, s33, 0
	global_load_dwordx4 v[152:155], v83, s[32:33]
	s_add_u32 s32, s32, 0x2400
	s_addc_u32 s33, s33, 0
	global_load_dwordx4 v[160:163], v83, s[32:33]
	s_add_u32 s32, s32, 0x2400
	s_addc_u32 s33, s33, 0
	global_load_dwordx4 v[164:167], v83, s[32:33]
	s_add_u32 s32, s32, 0x2400
	s_addc_u32 s33, s33, 0
	global_load_dwordx4 v[172:175], v83, s[32:33]
	s_add_u32 s32, s32, 0x2400
	s_addc_u32 s33, s33, 0
	global_load_dwordx4 v[176:179], v83, s[32:33]
	ds_read_b128 v[180:183], v129 offset:0
	ds_read_b128 v[184:187], v129 offset:1024
	ds_read_b128 v[188:191], v129 offset:2048
	ds_read_b128 v[192:195], v129 offset:3072
	ds_read_b128 v[196:199], v129 offset:4096
	ds_read_b128 v[200:203], v129 offset:5120
	ds_read_b128 v[204:207], v129 offset:6144
	ds_read_b128 v[208:211], v129 offset:7168
	ds_read_b128 v[212:215], v129 offset:8192
	ds_read_b128 v[216:219], v129 offset:9216
	ds_read_b128 v[228:231], v129 offset:10240
	ds_read_b128 v[232:235], v129 offset:11264
	s_waitcnt vmcnt(31)
	s_waitcnt lgkmcnt(9)
	v_mfma_f32_16x16x32_bf16 v[16:19], v[28:31], v[180:183], v[16:19]
	v_mfma_f32_16x16x32_bf16 v[20:23], v[28:31], v[184:187], v[20:23]
	v_mfma_f32_16x16x32_bf16 v[24:27], v[28:31], v[188:191], v[24:27]
	ds_read_b128 v[180:183], v129 offset:12288
	ds_read_b128 v[184:187], v129 offset:13312
	ds_read_b128 v[188:191], v129 offset:14336
	s_waitcnt vmcnt(30)
	s_waitcnt lgkmcnt(9)
	v_mfma_f32_16x16x32_bf16 v[16:19], v[32:35], v[192:195], v[16:19]
	v_mfma_f32_16x16x32_bf16 v[20:23], v[32:35], v[196:199], v[20:23]
	v_mfma_f32_16x16x32_bf16 v[24:27], v[32:35], v[200:203], v[24:27]
	ds_read_b128 v[192:195], v129 offset:15360
	ds_read_b128 v[196:199], v129 offset:16384
	ds_read_b128 v[200:203], v129 offset:17408
	s_waitcnt vmcnt(29)
	s_waitcnt lgkmcnt(9)
	v_mfma_f32_16x16x32_bf16 v[16:19], v[36:39], v[204:207], v[16:19]
	v_mfma_f32_16x16x32_bf16 v[20:23], v[36:39], v[208:211], v[20:23]
	v_mfma_f32_16x16x32_bf16 v[24:27], v[36:39], v[212:215], v[24:27]
	ds_read_b128 v[204:207], v129 offset:18432
	ds_read_b128 v[208:211], v129 offset:19456
	ds_read_b128 v[212:215], v129 offset:20480
	s_waitcnt vmcnt(28)
	s_waitcnt lgkmcnt(9)
	v_mfma_f32_16x16x32_bf16 v[16:19], v[40:43], v[216:219], v[16:19]
	v_mfma_f32_16x16x32_bf16 v[20:23], v[40:43], v[228:231], v[20:23]
	v_mfma_f32_16x16x32_bf16 v[24:27], v[40:43], v[232:235], v[24:27]
	ds_read_b128 v[216:219], v129 offset:21504
	ds_read_b128 v[228:231], v129 offset:22528
	ds_read_b128 v[232:235], v129 offset:23552
	s_waitcnt vmcnt(27)
	s_waitcnt lgkmcnt(9)
	v_mfma_f32_16x16x32_bf16 v[16:19], v[44:47], v[180:183], v[16:19]
	v_mfma_f32_16x16x32_bf16 v[20:23], v[44:47], v[184:187], v[20:23]
	v_mfma_f32_16x16x32_bf16 v[24:27], v[44:47], v[188:191], v[24:27]
	ds_read_b128 v[180:183], v129 offset:24576
	ds_read_b128 v[184:187], v129 offset:25600
	ds_read_b128 v[188:191], v129 offset:26624
	s_waitcnt vmcnt(26)
	s_waitcnt lgkmcnt(9)
	v_mfma_f32_16x16x32_bf16 v[16:19], v[48:51], v[192:195], v[16:19]
	v_mfma_f32_16x16x32_bf16 v[20:23], v[48:51], v[196:199], v[20:23]
	v_mfma_f32_16x16x32_bf16 v[24:27], v[48:51], v[200:203], v[24:27]
	ds_read_b128 v[192:195], v129 offset:27648
	ds_read_b128 v[196:199], v129 offset:28672
	ds_read_b128 v[200:203], v129 offset:29696
	s_waitcnt vmcnt(25)
	s_waitcnt lgkmcnt(9)
	v_mfma_f32_16x16x32_bf16 v[16:19], v[52:55], v[204:207], v[16:19]
	v_mfma_f32_16x16x32_bf16 v[20:23], v[52:55], v[208:211], v[20:23]
	v_mfma_f32_16x16x32_bf16 v[24:27], v[52:55], v[212:215], v[24:27]
	ds_read_b128 v[204:207], v129 offset:30720
	ds_read_b128 v[208:211], v129 offset:31744
	ds_read_b128 v[212:215], v129 offset:32768
	s_waitcnt vmcnt(24)
	s_waitcnt lgkmcnt(9)
	v_mfma_f32_16x16x32_bf16 v[16:19], v[56:59], v[216:219], v[16:19]
	v_mfma_f32_16x16x32_bf16 v[20:23], v[56:59], v[228:231], v[20:23]
	v_mfma_f32_16x16x32_bf16 v[24:27], v[56:59], v[232:235], v[24:27]
	ds_read_b128 v[216:219], v129 offset:33792
	ds_read_b128 v[228:231], v129 offset:34816
	ds_read_b128 v[232:235], v129 offset:35840
	s_waitcnt vmcnt(23)
	s_waitcnt lgkmcnt(9)
	v_mfma_f32_16x16x32_bf16 v[16:19], v[60:63], v[180:183], v[16:19]
	v_mfma_f32_16x16x32_bf16 v[20:23], v[60:63], v[184:187], v[20:23]
	v_mfma_f32_16x16x32_bf16 v[24:27], v[60:63], v[188:191], v[24:27]
	ds_read_b128 v[180:183], v129 offset:36864
	ds_read_b128 v[184:187], v129 offset:37888
	ds_read_b128 v[188:191], v129 offset:38912
	s_waitcnt vmcnt(22)
	s_waitcnt lgkmcnt(9)
	v_mfma_f32_16x16x32_bf16 v[16:19], v[64:67], v[192:195], v[16:19]
	v_mfma_f32_16x16x32_bf16 v[20:23], v[64:67], v[196:199], v[20:23]
	v_mfma_f32_16x16x32_bf16 v[24:27], v[64:67], v[200:203], v[24:27]
	ds_read_b128 v[192:195], v129 offset:39936
	ds_read_b128 v[196:199], v129 offset:40960
	ds_read_b128 v[200:203], v129 offset:41984
	s_waitcnt vmcnt(21)
	s_waitcnt lgkmcnt(9)
	v_mfma_f32_16x16x32_bf16 v[16:19], v[68:71], v[204:207], v[16:19]
	v_mfma_f32_16x16x32_bf16 v[20:23], v[68:71], v[208:211], v[20:23]
	v_mfma_f32_16x16x32_bf16 v[24:27], v[68:71], v[212:215], v[24:27]
	ds_read_b128 v[204:207], v129 offset:43008
	ds_read_b128 v[208:211], v129 offset:44032
	ds_read_b128 v[212:215], v129 offset:45056
	s_waitcnt vmcnt(20)
	s_waitcnt lgkmcnt(9)
	v_mfma_f32_16x16x32_bf16 v[16:19], v[72:75], v[216:219], v[16:19]
	v_mfma_f32_16x16x32_bf16 v[20:23], v[72:75], v[228:231], v[20:23]
	v_mfma_f32_16x16x32_bf16 v[24:27], v[72:75], v[232:235], v[24:27]
	ds_read_b128 v[216:219], v129 offset:46080
	ds_read_b128 v[228:231], v129 offset:47104
	ds_read_b128 v[232:235], v129 offset:48128
	s_waitcnt vmcnt(19)
	s_waitcnt lgkmcnt(9)
	v_mfma_f32_16x16x32_bf16 v[16:19], v[76:79], v[180:183], v[16:19]
	v_mfma_f32_16x16x32_bf16 v[20:23], v[76:79], v[184:187], v[20:23]
	v_mfma_f32_16x16x32_bf16 v[24:27], v[76:79], v[188:191], v[24:27]
	ds_read_b128 v[180:183], v130 offset:0
	ds_read_b128 v[184:187], v130 offset:1024
	ds_read_b128 v[188:191], v130 offset:2048
	s_waitcnt vmcnt(18)
	s_waitcnt lgkmcnt(9)
	v_mfma_f32_16x16x32_bf16 v[16:19], v[84:87], v[192:195], v[16:19]
	v_mfma_f32_16x16x32_bf16 v[20:23], v[84:87], v[196:199], v[20:23]
	v_mfma_f32_16x16x32_bf16 v[24:27], v[84:87], v[200:203], v[24:27]
	ds_read_b128 v[192:195], v130 offset:3072
	ds_read_b128 v[196:199], v130 offset:4096
	ds_read_b128 v[200:203], v130 offset:5120
	s_waitcnt vmcnt(17)
	s_waitcnt lgkmcnt(9)
	v_mfma_f32_16x16x32_bf16 v[16:19], v[88:91], v[204:207], v[16:19]
	v_mfma_f32_16x16x32_bf16 v[20:23], v[88:91], v[208:211], v[20:23]
	v_mfma_f32_16x16x32_bf16 v[24:27], v[88:91], v[212:215], v[24:27]
	ds_read_b128 v[204:207], v130 offset:6144
	ds_read_b128 v[208:211], v130 offset:7168
	ds_read_b128 v[212:215], v130 offset:8192
	s_waitcnt vmcnt(16)
	s_waitcnt lgkmcnt(9)
	v_mfma_f32_16x16x32_bf16 v[16:19], v[92:95], v[216:219], v[16:19]
	v_mfma_f32_16x16x32_bf16 v[20:23], v[92:95], v[228:231], v[20:23]
	v_mfma_f32_16x16x32_bf16 v[24:27], v[92:95], v[232:235], v[24:27]
	ds_read_b128 v[216:219], v130 offset:9216
	ds_read_b128 v[228:231], v130 offset:10240
	ds_read_b128 v[232:235], v130 offset:11264
	s_waitcnt vmcnt(15)
	s_waitcnt lgkmcnt(9)
	v_mfma_f32_16x16x32_bf16 v[16:19], v[96:99], v[180:183], v[16:19]
	v_mfma_f32_16x16x32_bf16 v[20:23], v[96:99], v[184:187], v[20:23]
	v_mfma_f32_16x16x32_bf16 v[24:27], v[96:99], v[188:191], v[24:27]
	ds_read_b128 v[180:183], v130 offset:12288
	ds_read_b128 v[184:187], v130 offset:13312
	ds_read_b128 v[188:191], v130 offset:14336
	s_waitcnt vmcnt(14)
	s_waitcnt lgkmcnt(9)
	v_mfma_f32_16x16x32_bf16 v[16:19], v[100:103], v[192:195], v[16:19]
	v_mfma_f32_16x16x32_bf16 v[20:23], v[100:103], v[196:199], v[20:23]
	v_mfma_f32_16x16x32_bf16 v[24:27], v[100:103], v[200:203], v[24:27]
	ds_read_b128 v[192:195], v130 offset:15360
	ds_read_b128 v[196:199], v130 offset:16384
	ds_read_b128 v[200:203], v130 offset:17408
	s_waitcnt vmcnt(13)
	s_waitcnt lgkmcnt(9)
	v_mfma_f32_16x16x32_bf16 v[16:19], v[104:107], v[204:207], v[16:19]
	v_mfma_f32_16x16x32_bf16 v[20:23], v[104:107], v[208:211], v[20:23]
	v_mfma_f32_16x16x32_bf16 v[24:27], v[104:107], v[212:215], v[24:27]
	ds_read_b128 v[204:207], v130 offset:18432
	ds_read_b128 v[208:211], v130 offset:19456
	ds_read_b128 v[212:215], v130 offset:20480
	s_waitcnt vmcnt(12)
	s_waitcnt lgkmcnt(9)
	v_mfma_f32_16x16x32_bf16 v[16:19], v[108:111], v[216:219], v[16:19]
	v_mfma_f32_16x16x32_bf16 v[20:23], v[108:111], v[228:231], v[20:23]
	v_mfma_f32_16x16x32_bf16 v[24:27], v[108:111], v[232:235], v[24:27]
	ds_read_b128 v[216:219], v130 offset:21504
	ds_read_b128 v[228:231], v130 offset:22528
	ds_read_b128 v[232:235], v130 offset:23552
	s_waitcnt vmcnt(11)
	s_waitcnt lgkmcnt(9)
	v_mfma_f32_16x16x32_bf16 v[16:19], v[112:115], v[180:183], v[16:19]
	v_mfma_f32_16x16x32_bf16 v[20:23], v[112:115], v[184:187], v[20:23]
	v_mfma_f32_16x16x32_bf16 v[24:27], v[112:115], v[188:191], v[24:27]
	ds_read_b128 v[180:183], v130 offset:24576
	ds_read_b128 v[184:187], v130 offset:25600
	ds_read_b128 v[188:191], v130 offset:26624
	s_waitcnt vmcnt(10)
	s_waitcnt lgkmcnt(9)
	v_mfma_f32_16x16x32_bf16 v[16:19], v[116:119], v[192:195], v[16:19]
	v_mfma_f32_16x16x32_bf16 v[20:23], v[116:119], v[196:199], v[20:23]
	v_mfma_f32_16x16x32_bf16 v[24:27], v[116:119], v[200:203], v[24:27]
	ds_read_b128 v[192:195], v130 offset:27648
	ds_read_b128 v[196:199], v130 offset:28672
	ds_read_b128 v[200:203], v130 offset:29696
	s_waitcnt vmcnt(9)
	s_waitcnt lgkmcnt(9)
	v_mfma_f32_16x16x32_bf16 v[16:19], v[120:123], v[204:207], v[16:19]
	v_mfma_f32_16x16x32_bf16 v[20:23], v[120:123], v[208:211], v[20:23]
	v_mfma_f32_16x16x32_bf16 v[24:27], v[120:123], v[212:215], v[24:27]
	ds_read_b128 v[204:207], v130 offset:30720
	ds_read_b128 v[208:211], v130 offset:31744
	ds_read_b128 v[212:215], v130 offset:32768
	s_waitcnt vmcnt(8)
	s_waitcnt lgkmcnt(9)
	v_mfma_f32_16x16x32_bf16 v[16:19], v[124:127], v[216:219], v[16:19]
	v_mfma_f32_16x16x32_bf16 v[20:23], v[124:127], v[228:231], v[20:23]
	v_mfma_f32_16x16x32_bf16 v[24:27], v[124:127], v[232:235], v[24:27]
	ds_read_b128 v[216:219], v130 offset:33792
	ds_read_b128 v[228:231], v130 offset:34816
	ds_read_b128 v[232:235], v130 offset:35840
	s_waitcnt vmcnt(7)
	s_waitcnt lgkmcnt(9)
	v_mfma_f32_16x16x32_bf16 v[16:19], v[140:143], v[180:183], v[16:19]
	v_mfma_f32_16x16x32_bf16 v[20:23], v[140:143], v[184:187], v[20:23]
	v_mfma_f32_16x16x32_bf16 v[24:27], v[140:143], v[188:191], v[24:27]
	ds_read_b128 v[180:183], v130 offset:36864
	ds_read_b128 v[184:187], v130 offset:37888
	ds_read_b128 v[188:191], v130 offset:38912
	s_waitcnt vmcnt(6)
	s_waitcnt lgkmcnt(9)
	v_mfma_f32_16x16x32_bf16 v[16:19], v[144:147], v[192:195], v[16:19]
	v_mfma_f32_16x16x32_bf16 v[20:23], v[144:147], v[196:199], v[20:23]
	v_mfma_f32_16x16x32_bf16 v[24:27], v[144:147], v[200:203], v[24:27]
	ds_read_b128 v[192:195], v130 offset:39936
	ds_read_b128 v[196:199], v130 offset:40960
	ds_read_b128 v[200:203], v130 offset:41984
	s_waitcnt vmcnt(5)
	s_waitcnt lgkmcnt(9)
	v_mfma_f32_16x16x32_bf16 v[16:19], v[148:151], v[204:207], v[16:19]
	v_mfma_f32_16x16x32_bf16 v[20:23], v[148:151], v[208:211], v[20:23]
	v_mfma_f32_16x16x32_bf16 v[24:27], v[148:151], v[212:215], v[24:27]
	ds_read_b128 v[204:207], v130 offset:43008
	ds_read_b128 v[208:211], v130 offset:44032
	ds_read_b128 v[212:215], v130 offset:45056
	s_waitcnt vmcnt(4)
	s_waitcnt lgkmcnt(9)
	v_mfma_f32_16x16x32_bf16 v[16:19], v[152:155], v[216:219], v[16:19]
	v_mfma_f32_16x16x32_bf16 v[20:23], v[152:155], v[228:231], v[20:23]
	v_mfma_f32_16x16x32_bf16 v[24:27], v[152:155], v[232:235], v[24:27]
	ds_read_b128 v[216:219], v130 offset:46080
	ds_read_b128 v[228:231], v130 offset:47104
	ds_read_b128 v[232:235], v130 offset:48128
	s_waitcnt vmcnt(3)
	s_waitcnt lgkmcnt(9)
	v_mfma_f32_16x16x32_bf16 v[16:19], v[160:163], v[180:183], v[16:19]
	v_mfma_f32_16x16x32_bf16 v[20:23], v[160:163], v[184:187], v[20:23]
	v_mfma_f32_16x16x32_bf16 v[24:27], v[160:163], v[188:191], v[24:27]
	s_waitcnt vmcnt(2)
	s_waitcnt lgkmcnt(6)
	v_mfma_f32_16x16x32_bf16 v[16:19], v[164:167], v[192:195], v[16:19]
	v_mfma_f32_16x16x32_bf16 v[20:23], v[164:167], v[196:199], v[20:23]
	v_mfma_f32_16x16x32_bf16 v[24:27], v[164:167], v[200:203], v[24:27]
	s_waitcnt vmcnt(1)
	s_waitcnt lgkmcnt(3)
	v_mfma_f32_16x16x32_bf16 v[16:19], v[172:175], v[204:207], v[16:19]
	v_mfma_f32_16x16x32_bf16 v[20:23], v[172:175], v[208:211], v[20:23]
	v_mfma_f32_16x16x32_bf16 v[24:27], v[172:175], v[212:215], v[24:27]
	s_waitcnt vmcnt(0)
	s_waitcnt lgkmcnt(0)
	v_mfma_f32_16x16x32_bf16 v[16:19], v[176:179], v[216:219], v[16:19]
	v_mfma_f32_16x16x32_bf16 v[20:23], v[176:179], v[228:231], v[20:23]
	v_mfma_f32_16x16x32_bf16 v[24:27], v[176:179], v[232:235], v[24:27]
.Lp0a2_odd_nb1:
	s_waitcnt lgkmcnt(0)
	s_barrier
	s_waitcnt vmcnt(0)
	v_lshrrev_b32_e32 v82, 4, v170
	v_lshlrev_b32_e32 v82, 2, v82
	s_lshl_b32 s73, s3, 4
	v_add_u32_e32 v82, s73, v82
	v_lshlrev_b32_e32 v82, 16, v82
	s_lshl_b32 s73, s95, 8
	v_add3_u32 v132, v82, v134, s73
	v_add_f32_e32 v180, v4, v236
	v_add_f32_e32 v181, v8, v237
	v_add_f32_e32 v182, v12, v238
	global_store_dwordx3 v132, v[180:182], s[14:15]
	v_add_f32_e32 v192, v5, v236
	v_add_f32_e32 v193, v9, v237
	v_add_f32_e32 v194, v13, v238
	v_add_u32_e32 v196, 0x10000, v132
	global_store_dwordx3 v196, v[192:194], s[14:15]
	v_add_f32_e32 v204, v6, v236
	v_add_f32_e32 v205, v10, v237
	v_add_f32_e32 v206, v14, v238
	v_add_u32_e32 v208, 0x20000, v132
	global_store_dwordx3 v208, v[204:206], s[14:15]
	v_add_f32_e32 v216, v7, v236
	v_add_f32_e32 v217, v11, v237
	v_add_f32_e32 v218, v15, v238
	v_add_u32_e32 v228, 0x30000, v132
	global_store_dwordx3 v228, v[216:218], s[14:15]
	s_cmp_lg_u32 s3, 0
	s_cbranch_scc1 .Lp0a2_odd_done
	s_mov_b64 exec, 0xffff
	s_lshl_b32 s73, s95, 8
	s_add_i32 s73, s73, 0x800000
	v_add_u32_e32 v132, s73, v134
	v_add_f32_e32 v188, v16, v236
	v_add_f32_e32 v189, v20, v237
	v_add_f32_e32 v190, v24, v238
	global_store_dwordx3 v132, v[188:190], s[14:15]
	v_add_f32_e32 v200, v17, v236
	v_add_f32_e32 v201, v21, v237
	v_add_f32_e32 v202, v25, v238
	v_add_u32_e32 v197, 0x10000, v132
	global_store_dwordx3 v197, v[200:202], s[14:15]
	v_add_f32_e32 v212, v18, v236
	v_add_f32_e32 v213, v22, v237
	v_add_f32_e32 v214, v26, v238
	v_add_u32_e32 v209, 0x20000, v132
	global_store_dwordx3 v209, v[212:214], s[14:15]
	v_add_f32_e32 v232, v19, v236
	v_add_f32_e32 v233, v23, v237
	v_add_f32_e32 v234, v27, v238
	v_add_u32_e32 v229, 0x30000, v132
	global_store_dwordx3 v229, v[232:234], s[14:15]
	s_mov_b64 exec, -1
.Lp0a2_odd_done:
	s_branch .LBB0_28

.LBB0_82:
	v_readlane_b32 s3, v255, 5
	v_readlane_b32 s0, v255, 0
	v_readlane_b32 s1, v255, 1
	s_sub_u32 s0, s0, 0xc8
	s_subb_u32 s1, s1, 0
	s_load_dwordx2 s[74:75], s[0:1], 0x38
	v_lshrrev_b32_e32 v82, 4, v170
	s_lshl_b32 s73, s3, 7
	v_lshl_add_u32 v80, v82, 3, s73
	v_lshlrev_b32_e32 v83, 4, v170
	s_mul_i32 s73, s3, 0x3000
	v_add_u32_e32 v128, s73, v83
	v_mov_b32_e32 v129, v83
	v_add_u32_e32 v130, 0xc000, v83
	v_and_b32_e32 v134, 15, v170
	v_mul_u32_u24_e32 v134, 12, v134
	v_mov_b32_e32 v4, 0
	v_mov_b32_e32 v16, 0
	v_mov_b32_e32 v5, 0
	v_mov_b32_e32 v17, 0
	v_mov_b32_e32 v6, 0
	v_mov_b32_e32 v18, 0
	v_mov_b32_e32 v7, 0
	v_mov_b32_e32 v19, 0
	v_mov_b32_e32 v8, 0
	v_mov_b32_e32 v20, 0
	v_mov_b32_e32 v9, 0
	v_mov_b32_e32 v21, 0
	v_mov_b32_e32 v10, 0
	v_mov_b32_e32 v22, 0
	v_mov_b32_e32 v11, 0
	v_mov_b32_e32 v23, 0
	v_mov_b32_e32 v12, 0
	v_mov_b32_e32 v24, 0
	v_mov_b32_e32 v13, 0
	v_mov_b32_e32 v25, 0
	v_mov_b32_e32 v14, 0
	v_mov_b32_e32 v26, 0
	v_mov_b32_e32 v15, 0
	v_mov_b32_e32 v27, 0
	s_waitcnt lgkmcnt(0)
	s_mul_i32 s73, s91, 0xc0
	v_add_u32_e32 v82, s73, v134
	global_load_dwordx3 v[236:238], v82, s[74:75]
	s_waitcnt vmcnt(0)
	v_add_u32_e32 v82, 0, v80
	v_mad_u64_u32 v[2:3], s[0:1], v82, s69, v[226:227]
	global_load_dwordx3 v[28:30], v[2:3], off nt
	v_add_u32_e32 v82, 1, v80
	v_mad_u64_u32 v[2:3], s[0:1], v82, s69, v[226:227]
	global_load_dwordx3 v[32:34], v[2:3], off nt
	v_add_u32_e32 v82, 2, v80
	v_mad_u64_u32 v[2:3], s[0:1], v82, s69, v[226:227]
	global_load_dwordx3 v[36:38], v[2:3], off nt
	v_add_u32_e32 v82, 3, v80
	v_mad_u64_u32 v[2:3], s[0:1], v82, s69, v[226:227]
	global_load_dwordx3 v[40:42], v[2:3], off nt
	v_add_u32_e32 v82, 4, v80
	v_mad_u64_u32 v[2:3], s[0:1], v82, s69, v[226:227]
	global_load_dwordx3 v[44:46], v[2:3], off nt
	v_add_u32_e32 v82, 5, v80
	v_mad_u64_u32 v[2:3], s[0:1], v82, s69, v[226:227]
	global_load_dwordx3 v[48:50], v[2:3], off nt
	v_add_u32_e32 v82, 6, v80
	v_mad_u64_u32 v[2:3], s[0:1], v82, s69, v[226:227]
	global_load_dwordx3 v[52:54], v[2:3], off nt
	v_add_u32_e32 v82, 7, v80
	v_mad_u64_u32 v[2:3], s[0:1], v82, s69, v[226:227]
	global_load_dwordx3 v[56:58], v[2:3], off nt
	v_add_u32_e32 v82, 32, v80
	v_mad_u64_u32 v[2:3], s[0:1], v82, s69, v[226:227]
	global_load_dwordx3 v[60:62], v[2:3], off nt
	v_add_u32_e32 v82, 33, v80
	v_mad_u64_u32 v[2:3], s[0:1], v82, s69, v[226:227]
	global_load_dwordx3 v[64:66], v[2:3], off nt
	v_add_u32_e32 v82, 34, v80
	v_mad_u64_u32 v[2:3], s[0:1], v82, s69, v[226:227]
	global_load_dwordx3 v[68:70], v[2:3], off nt
	v_add_u32_e32 v82, 35, v80
	v_mad_u64_u32 v[2:3], s[0:1], v82, s69, v[226:227]
	global_load_dwordx3 v[72:74], v[2:3], off nt
	v_add_u32_e32 v82, 36, v80
	v_mad_u64_u32 v[2:3], s[0:1], v82, s69, v[226:227]
	global_load_dwordx3 v[76:78], v[2:3], off nt
	v_add_u32_e32 v82, 37, v80
	v_mad_u64_u32 v[2:3], s[0:1], v82, s69, v[226:227]
	global_load_dwordx3 v[84:86], v[2:3], off nt
	v_add_u32_e32 v82, 38, v80
	v_mad_u64_u32 v[2:3], s[0:1], v82, s69, v[226:227]
	global_load_dwordx3 v[88:90], v[2:3], off nt
	v_add_u32_e32 v82, 39, v80
	v_mad_u64_u32 v[2:3], s[0:1], v82, s69, v[226:227]
	global_load_dwordx3 v[92:94], v[2:3], off nt
	v_add_u32_e32 v82, 64, v80
	v_mad_u64_u32 v[2:3], s[0:1], v82, s69, v[226:227]
	global_load_dwordx3 v[96:98], v[2:3], off nt
	v_add_u32_e32 v82, 65, v80
	v_mad_u64_u32 v[2:3], s[0:1], v82, s69, v[226:227]
	global_load_dwordx3 v[100:102], v[2:3], off nt
	v_add_u32_e32 v82, 66, v80
	v_mad_u64_u32 v[2:3], s[0:1], v82, s69, v[226:227]
	global_load_dwordx3 v[104:106], v[2:3], off nt
	v_add_u32_e32 v82, 67, v80
	v_mad_u64_u32 v[2:3], s[0:1], v82, s69, v[226:227]
	global_load_dwordx3 v[108:110], v[2:3], off nt
	v_add_u32_e32 v82, 68, v80
	v_mad_u64_u32 v[2:3], s[0:1], v82, s69, v[226:227]
	global_load_dwordx3 v[112:114], v[2:3], off nt
	v_add_u32_e32 v82, 69, v80
	v_mad_u64_u32 v[2:3], s[0:1], v82, s69, v[226:227]
	global_load_dwordx3 v[116:118], v[2:3], off nt
	v_add_u32_e32 v82, 70, v80
	v_mad_u64_u32 v[2:3], s[0:1], v82, s69, v[226:227]
	global_load_dwordx3 v[120:122], v[2:3], off nt
	v_add_u32_e32 v82, 71, v80
	v_mad_u64_u32 v[2:3], s[0:1], v82, s69, v[226:227]
	global_load_dwordx3 v[124:126], v[2:3], off nt
	v_add_u32_e32 v82, 96, v80
	v_mad_u64_u32 v[2:3], s[0:1], v82, s69, v[226:227]
	global_load_dwordx3 v[140:142], v[2:3], off nt
	v_add_u32_e32 v82, 97, v80
	v_mad_u64_u32 v[2:3], s[0:1], v82, s69, v[226:227]
	global_load_dwordx3 v[144:146], v[2:3], off nt
	v_add_u32_e32 v82, 98, v80
	v_mad_u64_u32 v[2:3], s[0:1], v82, s69, v[226:227]
	global_load_dwordx3 v[148:150], v[2:3], off nt
	v_add_u32_e32 v82, 99, v80
	v_mad_u64_u32 v[2:3], s[0:1], v82, s69, v[226:227]
	global_load_dwordx3 v[152:154], v[2:3], off nt
	v_add_u32_e32 v82, 100, v80
	v_mad_u64_u32 v[2:3], s[0:1], v82, s69, v[226:227]
	global_load_dwordx3 v[160:162], v[2:3], off nt
	v_add_u32_e32 v82, 101, v80
	v_mad_u64_u32 v[2:3], s[0:1], v82, s69, v[226:227]
	global_load_dwordx3 v[164:166], v[2:3], off nt
	v_add_u32_e32 v82, 102, v80
	v_mad_u64_u32 v[2:3], s[0:1], v82, s69, v[226:227]
	global_load_dwordx3 v[172:174], v[2:3], off nt
	v_add_u32_e32 v82, 103, v80
	v_mad_u64_u32 v[2:3], s[0:1], v82, s69, v[226:227]
	global_load_dwordx3 v[176:178], v[2:3], off nt
	s_waitcnt vmcnt(24)
	v_cvt_pk_bf16_f32 v180, v28, v32
	v_cvt_pk_bf16_f32 v181, v36, v40
	v_cvt_pk_bf16_f32 v182, v44, v48
	v_cvt_pk_bf16_f32 v183, v52, v56
	v_cvt_pk_bf16_f32 v184, v29, v33
	v_cvt_pk_bf16_f32 v185, v37, v41
	v_cvt_pk_bf16_f32 v186, v45, v49
	v_cvt_pk_bf16_f32 v187, v53, v57
	v_cvt_pk_bf16_f32 v188, v30, v34
	v_cvt_pk_bf16_f32 v189, v38, v42
	v_cvt_pk_bf16_f32 v190, v46, v50
	v_cvt_pk_bf16_f32 v191, v54, v58
	ds_write_b128 v128, v[180:183] offset:0
	ds_write_b128 v128, v[184:187] offset:1024
	ds_write_b128 v128, v[188:191] offset:2048
	s_waitcnt vmcnt(16)
	v_cvt_pk_bf16_f32 v192, v60, v64
	v_cvt_pk_bf16_f32 v193, v68, v72
	v_cvt_pk_bf16_f32 v194, v76, v84
	v_cvt_pk_bf16_f32 v195, v88, v92
	v_cvt_pk_bf16_f32 v196, v61, v65
	v_cvt_pk_bf16_f32 v197, v69, v73
	v_cvt_pk_bf16_f32 v198, v77, v85
	v_cvt_pk_bf16_f32 v199, v89, v93
	v_cvt_pk_bf16_f32 v200, v62, v66
	v_cvt_pk_bf16_f32 v201, v70, v74
	v_cvt_pk_bf16_f32 v202, v78, v86
	v_cvt_pk_bf16_f32 v203, v90, v94
	ds_write_b128 v128, v[192:195] offset:3072
	ds_write_b128 v128, v[196:199] offset:4096
	ds_write_b128 v128, v[200:203] offset:5120
	s_waitcnt vmcnt(8)
	v_cvt_pk_bf16_f32 v204, v96, v100
	v_cvt_pk_bf16_f32 v205, v104, v108
	v_cvt_pk_bf16_f32 v206, v112, v116
	v_cvt_pk_bf16_f32 v207, v120, v124
	v_cvt_pk_bf16_f32 v208, v97, v101
	v_cvt_pk_bf16_f32 v209, v105, v109
	v_cvt_pk_bf16_f32 v210, v113, v117
	v_cvt_pk_bf16_f32 v211, v121, v125
	v_cvt_pk_bf16_f32 v212, v98, v102
	v_cvt_pk_bf16_f32 v213, v106, v110
	v_cvt_pk_bf16_f32 v214, v114, v118
	v_cvt_pk_bf16_f32 v215, v122, v126
	ds_write_b128 v128, v[204:207] offset:6144
	ds_write_b128 v128, v[208:211] offset:7168
	ds_write_b128 v128, v[212:215] offset:8192
	s_waitcnt vmcnt(0)
	v_cvt_pk_bf16_f32 v216, v140, v144
	v_cvt_pk_bf16_f32 v217, v148, v152
	v_cvt_pk_bf16_f32 v218, v160, v164
	v_cvt_pk_bf16_f32 v219, v172, v176
	v_cvt_pk_bf16_f32 v228, v141, v145
	v_cvt_pk_bf16_f32 v229, v149, v153
	v_cvt_pk_bf16_f32 v230, v161, v165
	v_cvt_pk_bf16_f32 v231, v173, v177
	v_cvt_pk_bf16_f32 v232, v142, v146
	v_cvt_pk_bf16_f32 v233, v150, v154
	v_cvt_pk_bf16_f32 v234, v162, v166
	v_cvt_pk_bf16_f32 v235, v174, v178
	ds_write_b128 v128, v[216:219] offset:9216
	ds_write_b128 v128, v[228:231] offset:10240
	ds_write_b128 v128, v[232:235] offset:11264
	s_waitcnt lgkmcnt(0)
	s_cmp_lg_u32 s3, 0
	s_cbranch_scc1 .Lp0a2_even_sync
	v_mov_b32_e32 v132, 0x3f00
	s_mov_b32 s73, 0

.Lp0a2_even_nb1:
	s_waitcnt lgkmcnt(0)
	s_barrier
	s_waitcnt vmcnt(0)
	v_lshrrev_b32_e32 v82, 4, v170
	v_lshlrev_b32_e32 v82, 2, v82
	s_lshl_b32 s73, s3, 4
	v_add_u32_e32 v82, s73, v82
	v_lshlrev_b32_e32 v82, 16, v82
	s_lshl_b32 s73, s91, 8
	v_add3_u32 v132, v82, v134, s73
	v_add_f32_e32 v180, v4, v236
	v_add_f32_e32 v181, v8, v237
	v_add_f32_e32 v182, v12, v238
	global_store_dwordx3 v132, v[180:182], s[14:15]
	v_add_f32_e32 v192, v5, v236
	v_add_f32_e32 v193, v9, v237
	v_add_f32_e32 v194, v13, v238
	v_add_u32_e32 v196, 0x10000, v132
	global_store_dwordx3 v196, v[192:194], s[14:15]
	v_add_f32_e32 v204, v6, v236
	v_add_f32_e32 v205, v10, v237
	v_add_f32_e32 v206, v14, v238
	v_add_u32_e32 v208, 0x20000, v132
	global_store_dwordx3 v208, v[204:206], s[14:15]
	v_add_f32_e32 v216, v7, v236
	v_add_f32_e32 v217, v11, v237
	v_add_f32_e32 v218, v15, v238
	v_add_u32_e32 v228, 0x30000, v132
	global_store_dwordx3 v228, v[216:218], s[14:15]
	s_cmp_lg_u32 s3, 0
	s_cbranch_scc1 .Lp0a2_even_done
	s_mov_b64 exec, 0xffff
	s_lshl_b32 s73, s91, 8
	s_add_i32 s73, s73, 0x800000
	v_add_u32_e32 v132, s73, v134
	v_add_f32_e32 v188, v16, v236
	v_add_f32_e32 v189, v20, v237
	v_add_f32_e32 v190, v24, v238
	global_store_dwordx3 v132, v[188:190], s[14:15]
	v_add_f32_e32 v200, v17, v236
	v_add_f32_e32 v201, v21, v237
	v_add_f32_e32 v202, v25, v238
	v_add_u32_e32 v197, 0x10000, v132
	global_store_dwordx3 v197, v[200:202], s[14:15]
	v_add_f32_e32 v212, v18, v236
	v_add_f32_e32 v213, v22, v237
	v_add_f32_e32 v214, v26, v238
	v_add_u32_e32 v209, 0x20000, v132
	global_store_dwordx3 v209, v[212:214], s[14:15]
	v_add_f32_e32 v232, v19, v236
	v_add_f32_e32 v233, v23, v237
	v_add_f32_e32 v234, v27, v238
	v_add_u32_e32 v229, 0x30000, v132
	global_store_dwordx3 v229, v[232:234], s[14:15]
	s_mov_b64 exec, -1
